# PLE-gate epilogue (even layers 0,2): dwordx2 load/store pairs merged into dwordx4 via v_permlane16_swap
# baseline (speedup 1.0000x reference)
.LBB0_898:
	v_lshl_add_u32 v142, s12, 8, v150
	v_ashrrev_i32_e32 v143, 31, v142
	v_lshlrev_b64 v[144:145], 6, v[142:143]
	v_lshl_add_u64 v[146:147], s[10:11], 0, v[144:145]
	v_bfe_u32 v166, v206, 4, 2
	v_lshlrev_b32_e32 v166, 4, v166
	v_mov_b32_e32 v167, 0
	v_lshl_add_u64 v[162:163], v[146:147], 0, v[166:167]
	global_load_dwordx4 v[158:161], v[162:163], off
	v_lshl_or_b32 v140, s2, 8, v152
	v_ashrrev_i32_e32 v141, 31, v140
	v_lshlrev_b64 v[146:147], 10, v[142:143]
	v_lshl_add_u64 v[146:147], v[146:147], 0, v[140:141]
	v_lshlrev_b64 v[146:147], 1, v[146:147]
	v_lshl_add_u64 v[148:149], s[20:21], 0, v[146:147]
	v_bfe_u32 v228, v206, 4, 1
	v_mul_u32_u24_e32 v228, 24, v228
	v_mov_b32_e32 v229, 0
	v_lshl_add_u64 v[230:231], v[148:149], 0, v[228:229]
	global_load_dwordx4 v[184:187], v[230:231], off
	v_lshl_add_u64 v[148:149], s[8:9], 0, v[146:147]
	v_bfe_u32 v228, v206, 4, 1
	v_mul_u32_u24_e32 v228, 24, v228
	v_mov_b32_e32 v229, 0
	v_lshl_add_u64 v[230:231], v[148:149], 0, v[228:229]
	global_load_dwordx4 v[188:191], v[230:231], off
	v_lshl_add_u64 v[178:179], s[16:17], 0, v[146:147]
	v_or_b32_e32 v180, 32, v146
	v_mov_b32_e32 v181, v147
	s_lshl_b32 s36, s2, 2
	s_ashr_i32 s37, s36, 31
	s_waitcnt vmcnt(0)
	v_permlane16_swap_b32_e32 v184, v186
	v_permlane16_swap_b32_e32 v185, v187
	v_permlane16_swap_b32_e32 v188, v190
	v_permlane16_swap_b32_e32 v189, v191
	v_add_f32_e32 v162, v158, v159
	v_add_f32_e32 v163, v160, v161
	v_add_f32_e32 v162, v162, v163
	ds_swizzle_b32 v163, v162 offset:swizzle(SWAP,16)
	s_waitcnt lgkmcnt(0)
	v_add_f32_e32 v162, v162, v163
	v_mov_b32_e32 v163, v162
	s_nop 1
	v_permlane32_swap_b32_e32 v162, v163
	v_add_f32_e32 v170, v162, v163
	v_lshlrev_b32_e32 v164, 16, v185
	v_lshlrev_b32_e32 v160, 16, v184
	v_mov_b32_e32 v143, v170
	v_fmamk_f32 v143, v143, 0x3a800000, v156
	v_mul_f32_e32 v157, 0x4b800000, v143
	v_cmp_gt_f32_e32 vcc, s56, v143
	v_and_b32_e32 v161, 0xffff0000, v184
	v_and_b32_e32 v165, 0xffff0000, v185
	v_cndmask_b32_e32 v143, v143, v157, vcc
	v_rsq_f32_e32 v143, v143
	v_lshlrev_b32_e32 v158, 16, v188
	v_and_b32_e32 v159, 0xffff0000, v188
	v_lshlrev_b32_e32 v162, 16, v189
	v_mul_f32_e32 v157, 0x45800000, v143
	v_cndmask_b32_e32 v143, v143, v157, vcc
	v_mul_f32_e32 v124, v124, v143
	v_mul_f32_e32 v125, v125, v143
	v_mul_f32_e32 v126, v126, v143
	v_mul_f32_e32 v127, v127, v143
	v_mul_f32_e32 v124, 0xbfb8aa3b, v124
	v_mul_f32_e32 v125, 0xbfb8aa3b, v125
	v_mul_f32_e32 v126, 0xbfb8aa3b, v126
	v_mul_f32_e32 v127, 0xbfb8aa3b, v127
	v_exp_f32_e32 v124, v124
	v_exp_f32_e32 v125, v125
	v_exp_f32_e32 v126, v126
	v_exp_f32_e32 v127, v127
	v_add_f32_e32 v124, 1.0, v124
	v_add_f32_e32 v157, 1.0, v125
	v_add_f32_e32 v125, 1.0, v126
	v_add_f32_e32 v127, 1.0, v127
	v_rcp_f32_e32 v126, v124
	v_rcp_f32_e32 v124, v125
	v_rcp_f32_e32 v125, v127
	v_rcp_f32_e32 v127, v157
	v_and_b32_e32 v163, 0xffff0000, v189
	v_mul_f32_e32 v120, v120, v143
	v_pk_fma_f32 v[124:125], v[124:125], v[164:165], v[162:163]
	v_pk_fma_f32 v[126:127], v[126:127], v[160:161], v[158:159]
	v_lshl_add_u64 v[162:163], s[20:21], 0, v[180:181]
	v_cvt_pk_bf16_f32 v158, v126, v127
	v_cvt_pk_bf16_f32 v159, v124, v125
	v_mov_b32_e32 v220, v158
	v_mov_b32_e32 v221, v159
	v_mul_f32_e32 v121, v121, v143
	v_mul_f32_e32 v122, v122, v143
	v_mul_f32_e32 v123, v123, v143
	v_mul_f32_e32 v120, 0xbfb8aa3b, v120
	v_mul_f32_e32 v121, 0xbfb8aa3b, v121
	v_mul_f32_e32 v122, 0xbfb8aa3b, v122
	v_mul_f32_e32 v123, 0xbfb8aa3b, v123
	v_exp_f32_e32 v120, v120
	v_exp_f32_e32 v121, v121
	v_exp_f32_e32 v122, v122
	v_exp_f32_e32 v123, v123
	v_add_f32_e32 v120, 1.0, v120
	v_add_f32_e32 v121, 1.0, v121
	v_add_f32_e32 v122, 1.0, v122
	v_add_f32_e32 v123, 1.0, v123
	v_rcp_f32_e32 v120, v120
	v_rcp_f32_e32 v121, v121
	v_rcp_f32_e32 v122, v122
	v_rcp_f32_e32 v123, v123
	v_or_b32_e32 v162, 0x100, v146
	v_mov_b32_e32 v163, v147
	v_mul_f32_e32 v118, v118, v143
	v_mul_f32_e32 v119, v119, v143
	v_mul_f32_e32 v116, v116, v143
	v_mul_f32_e32 v117, v117, v143
	v_mul_f32_e32 v118, 0xbfb8aa3b, v118
	v_mul_f32_e32 v119, 0xbfb8aa3b, v119
	v_mul_f32_e32 v116, 0xbfb8aa3b, v116
	v_mul_f32_e32 v117, 0xbfb8aa3b, v117
	v_exp_f32_e32 v118, v118
	v_exp_f32_e32 v119, v119
	v_exp_f32_e32 v116, v116
	v_exp_f32_e32 v117, v117
	v_add_f32_e32 v118, 1.0, v118
	v_add_f32_e32 v119, 1.0, v119
	v_add_f32_e32 v116, 1.0, v116
	v_add_f32_e32 v117, 1.0, v117
	v_rcp_f32_e32 v118, v118
	v_rcp_f32_e32 v119, v119
	v_rcp_f32_e32 v116, v116
	v_rcp_f32_e32 v117, v117
	v_or_b32_e32 v146, 0x120, v146
	v_mul_f32_e32 v112, v112, v143
	v_mul_f32_e32 v113, v113, v143
	v_mul_f32_e32 v114, v114, v143
	v_mul_f32_e32 v115, v115, v143
	v_mul_f32_e32 v112, 0xbfb8aa3b, v112
	v_mul_f32_e32 v113, 0xbfb8aa3b, v113
	v_mul_f32_e32 v114, 0xbfb8aa3b, v114
	v_mul_f32_e32 v115, 0xbfb8aa3b, v115
	v_exp_f32_e32 v112, v112
	v_exp_f32_e32 v113, v113
	v_exp_f32_e32 v114, v114
	v_exp_f32_e32 v115, v115
	v_add_f32_e32 v112, 1.0, v112
	v_add_f32_e32 v113, 1.0, v113
	v_add_f32_e32 v114, 1.0, v114
	v_add_f32_e32 v115, 1.0, v115
	v_mul_f32_e32 v127, v127, v127
	v_mul_f32_e32 v125, v125, v125
	v_rcp_f32_e32 v112, v112
	v_rcp_f32_e32 v113, v113
	v_rcp_f32_e32 v114, v114
	v_rcp_f32_e32 v115, v115
	v_fmac_f32_e32 v127, v126, v126
	v_fmac_f32_e32 v125, v124, v124
	v_add_f32_e32 v124, v127, v125
	s_waitcnt vmcnt(0)
	v_lshlrev_b32_e32 v164, 16, v190
	v_and_b32_e32 v165, 0xffff0000, v190
	s_waitcnt vmcnt(0)
	v_lshlrev_b32_e32 v166, 16, v186
	v_and_b32_e32 v167, 0xffff0000, v186
	v_lshlrev_b32_e32 v160, 16, v191
	v_and_b32_e32 v161, 0xffff0000, v191
	v_lshlrev_b32_e32 v158, 16, v187
	v_and_b32_e32 v159, 0xffff0000, v187
	v_pk_fma_f32 v[120:121], v[120:121], v[166:167], v[164:165]
	v_lshl_add_u64 v[164:165], s[16:17], 0, v[180:181]
	v_pk_fma_f32 v[122:123], v[122:123], v[158:159], v[160:161]
	v_cvt_pk_bf16_f32 v158, v120, v121
	v_lshl_add_u64 v[166:167], s[20:21], 0, v[162:163]
	v_cvt_pk_bf16_f32 v159, v122, v123
	v_mov_b32_e32 v222, v158
	v_mov_b32_e32 v223, v159
	v_bfe_u32 v228, v206, 4, 1
	v_mul_u32_u24_e32 v228, 24, v228
	v_mov_b32_e32 v229, 0
	v_lshl_add_u64 v[230:231], v[164:165], 0, v[228:229]
	v_permlane16_swap_b32_e32 v220, v222
	v_permlane16_swap_b32_e32 v221, v223
	global_store_dwordx4 v[230:231], v[220:223], off offset:-32
	v_bfe_u32 v228, v206, 4, 1
	v_mul_u32_u24_e32 v228, 24, v228
	v_mov_b32_e32 v229, 0
	v_lshl_add_u64 v[230:231], v[148:149], 0, v[228:229]
	global_load_dwordx4 v[192:195], v[230:231], off offset:256
	v_mul_f32_e32 v121, v121, v121
	v_bfe_u32 v228, v206, 4, 1
	v_mul_u32_u24_e32 v228, 24, v228
	v_mov_b32_e32 v229, 0
	v_lshl_add_u64 v[230:231], v[166:167], 0, v[228:229]
	global_load_dwordx4 v[196:199], v[230:231], off
	v_mul_f32_e32 v123, v123, v123
	v_fmac_f32_e32 v121, v120, v120
	v_fmac_f32_e32 v123, v122, v122
	v_add_f32_e32 v120, v121, v123
	v_add_f32_e32 v120, v124, v120
	s_waitcnt vmcnt(0)
	v_permlane16_swap_b32_e32 v192, v194
	v_permlane16_swap_b32_e32 v193, v195
	v_permlane16_swap_b32_e32 v196, v198
	v_permlane16_swap_b32_e32 v197, v199
	v_lshlrev_b32_e32 v164, 16, v192
	v_and_b32_e32 v165, 0xffff0000, v192
	v_lshlrev_b32_e32 v160, 16, v193
	v_and_b32_e32 v161, 0xffff0000, v193
	s_waitcnt vmcnt(0)
	v_lshlrev_b32_e32 v166, 16, v196
	v_and_b32_e32 v167, 0xffff0000, v196
	v_lshlrev_b32_e32 v158, 16, v197
	v_and_b32_e32 v159, 0xffff0000, v197
	v_pk_fma_f32 v[118:119], v[118:119], v[158:159], v[160:161]
	v_lshl_add_u64 v[160:161], s[16:17], 0, v[162:163]
	v_pk_fma_f32 v[116:117], v[116:117], v[166:167], v[164:165]
	v_lshl_add_u64 v[162:163], s[20:21], 0, v[146:147]
	v_cvt_pk_bf16_f32 v158, v116, v117
	v_cvt_pk_bf16_f32 v159, v118, v119
	v_mov_b32_e32 v224, v158
	v_mov_b32_e32 v225, v159
	v_mul_f32_e32 v117, v117, v117
	v_mul_f32_e32 v119, v119, v119
	v_fmac_f32_e32 v117, v116, v116
	v_fmac_f32_e32 v119, v118, v118
	v_add_f32_e32 v116, v117, v119
	v_add_f32_e32 v124, v116, v120
	s_waitcnt vmcnt(0)
	v_lshlrev_b32_e32 v116, 16, v194
	v_and_b32_e32 v117, 0xffff0000, v194
	v_lshlrev_b32_e32 v118, 16, v195
	v_and_b32_e32 v119, 0xffff0000, v195
	s_waitcnt vmcnt(0)
	v_lshlrev_b32_e32 v120, 16, v198
	v_and_b32_e32 v121, 0xffff0000, v198
	v_lshlrev_b32_e32 v122, 16, v199
	v_and_b32_e32 v123, 0xffff0000, v199
	v_pk_fma_f32 v[114:115], v[114:115], v[122:123], v[118:119]
	v_pk_fma_f32 v[112:113], v[112:113], v[120:121], v[116:117]
	v_mul_f32_e32 v117, v115, v115
	v_mul_f32_e32 v116, v113, v113
	v_fmac_f32_e32 v116, v112, v112
	v_fmac_f32_e32 v117, v114, v114
	v_add_f32_e32 v116, v116, v117
	v_add_f32_e32 v118, v124, v116
	ds_swizzle_b32 v119, v118 offset:swizzle(SWAP,16)
	v_lshl_add_u64 v[116:117], s[16:17], 0, v[146:147]
	v_cvt_pk_bf16_f32 v112, v112, v113
	v_cvt_pk_bf16_f32 v113, v114, v115
	v_mov_b32_e32 v226, v112
	v_mov_b32_e32 v227, v113
	v_bfe_u32 v228, v206, 4, 1
	v_mul_u32_u24_e32 v228, 24, v228
	v_mov_b32_e32 v229, 0
	v_lshl_add_u64 v[230:231], v[116:117], 0, v[228:229]
	v_permlane16_swap_b32_e32 v224, v226
	v_permlane16_swap_b32_e32 v225, v227
	global_store_dwordx4 v[230:231], v[224:227], off offset:-32
	s_waitcnt lgkmcnt(0)
	v_add_f32_e32 v112, v118, v119
	v_mov_b32_e32 v113, v112
	s_nop 1
	v_permlane32_swap_b32_e32 v112, v113
	s_and_saveexec_b64 s[2:3], s[4:5]
	s_cbranch_execz .LBB0_900
	v_add_f32_e32 v114, v112, v113
	v_lshl_add_u64 v[112:113], s[18:19], 0, v[144:145]
	v_lshl_add_u64 v[112:113], s[36:37], 2, v[112:113]
	s_lshl_b32 s12, s50, 2
	v_lshl_add_u64 v[112:113], v[112:113], 0, s[12:13]
	global_store_dword v[112:113], v114, off
.LBB0_900:
	s_or_b64 exec, exec, s[2:3]
	v_or_b32_e32 v114, 16, v142
	v_ashrrev_i32_e32 v115, 31, v114
	v_lshlrev_b64 v[112:113], 6, v[114:115]
	v_lshl_add_u64 v[116:117], s[10:11], 0, v[112:113]
	v_bfe_u32 v144, v206, 4, 2
	v_lshlrev_b32_e32 v144, 4, v144
	v_mov_b32_e32 v145, 0
	v_lshl_add_u64 v[122:123], v[116:117], 0, v[144:145]
	global_load_dwordx4 v[118:121], v[122:123], off
	v_lshlrev_b64 v[114:115], 10, v[114:115]
	v_lshl_add_u64 v[114:115], v[114:115], 0, v[140:141]
	v_lshlrev_b64 v[114:115], 1, v[114:115]
	v_lshl_add_u64 v[116:117], s[20:21], 0, v[114:115]
	v_bfe_u32 v228, v206, 4, 1
	v_mul_u32_u24_e32 v228, 24, v228
	v_mov_b32_e32 v229, 0
	v_lshl_add_u64 v[230:231], v[116:117], 0, v[228:229]
	global_load_dwordx4 v[200:203], v[230:231], off
	v_lshl_add_u64 v[116:117], s[8:9], 0, v[114:115]
	v_bfe_u32 v228, v206, 4, 1
	v_mul_u32_u24_e32 v228, 24, v228
	v_mov_b32_e32 v229, 0
	v_lshl_add_u64 v[230:231], v[116:117], 0, v[228:229]
	global_load_dwordx4 v[208:211], v[230:231], off
	v_lshl_add_u64 v[162:163], s[16:17], 0, v[114:115]
	v_or_b32_e32 v164, 32, v114
	v_mov_b32_e32 v165, v115
	s_waitcnt vmcnt(0)
	v_permlane16_swap_b32_e32 v200, v202
	v_permlane16_swap_b32_e32 v201, v203
	v_permlane16_swap_b32_e32 v208, v210
	v_permlane16_swap_b32_e32 v209, v211
	v_add_f32_e32 v122, v118, v119
	v_add_f32_e32 v123, v120, v121
	v_add_f32_e32 v122, v122, v123
	ds_swizzle_b32 v123, v122 offset:swizzle(SWAP,16)
	s_waitcnt lgkmcnt(0)
	v_add_f32_e32 v122, v122, v123
	v_mov_b32_e32 v123, v122
	s_nop 1
	v_permlane32_swap_b32_e32 v122, v123
	v_add_f32_e32 v158, v122, v123
	v_lshlrev_b32_e32 v124, 16, v201
	v_lshlrev_b32_e32 v120, 16, v200
	v_mov_b32_e32 v118, v158
	v_fmamk_f32 v118, v118, 0x3a800000, v156
	v_mul_f32_e32 v119, 0x4b800000, v118
	v_cmp_gt_f32_e32 vcc, s56, v118
	v_and_b32_e32 v121, 0xffff0000, v200
	v_and_b32_e32 v125, 0xffff0000, v201
	v_cndmask_b32_e32 v118, v118, v119, vcc
	v_rsq_f32_e32 v122, v118
	s_waitcnt vmcnt(0)
	v_lshlrev_b32_e32 v118, 16, v208
	v_and_b32_e32 v119, 0xffff0000, v208
	v_mul_f32_e32 v123, 0x45800000, v122
	v_cndmask_b32_e32 v143, v122, v123, vcc
	v_mul_f32_e32 v108, v108, v143
	v_mul_f32_e32 v109, v109, v143
	v_mul_f32_e32 v110, v110, v143
	v_mul_f32_e32 v111, v111, v143
	v_mul_f32_e32 v108, 0xbfb8aa3b, v108
	v_mul_f32_e32 v109, 0xbfb8aa3b, v109
	v_mul_f32_e32 v110, 0xbfb8aa3b, v110
	v_mul_f32_e32 v111, 0xbfb8aa3b, v111
	v_exp_f32_e32 v108, v108
	v_exp_f32_e32 v109, v109
	v_exp_f32_e32 v110, v110
	v_exp_f32_e32 v111, v111
	v_add_f32_e32 v108, 1.0, v108
	v_add_f32_e32 v122, 1.0, v109
	v_add_f32_e32 v109, 1.0, v110
	v_add_f32_e32 v111, 1.0, v111
	v_rcp_f32_e32 v110, v108
	v_rcp_f32_e32 v108, v109
	v_rcp_f32_e32 v109, v111
	v_rcp_f32_e32 v111, v122
	v_lshlrev_b32_e32 v122, 16, v209
	v_and_b32_e32 v123, 0xffff0000, v209
	v_pk_fma_f32 v[108:109], v[108:109], v[124:125], v[122:123]
	v_pk_fma_f32 v[110:111], v[110:111], v[120:121], v[118:119]
	v_lshl_add_u64 v[122:123], s[20:21], 0, v[164:165]
	v_cvt_pk_bf16_f32 v118, v110, v111
	v_cvt_pk_bf16_f32 v119, v108, v109
	v_mov_b32_e32 v220, v118
	v_mov_b32_e32 v221, v119
	v_mul_f32_e32 v104, v104, v143
	v_mul_f32_e32 v105, v105, v143
	v_mul_f32_e32 v106, v106, v143
	v_mul_f32_e32 v107, v107, v143
	v_mul_f32_e32 v104, 0xbfb8aa3b, v104
	v_mul_f32_e32 v105, 0xbfb8aa3b, v105
	v_mul_f32_e32 v106, 0xbfb8aa3b, v106
	v_mul_f32_e32 v107, 0xbfb8aa3b, v107
	v_exp_f32_e32 v104, v104
	v_exp_f32_e32 v105, v105
	v_exp_f32_e32 v106, v106
	v_exp_f32_e32 v107, v107
	v_add_f32_e32 v104, 1.0, v104
	v_add_f32_e32 v105, 1.0, v105
	v_add_f32_e32 v106, 1.0, v106
	v_add_f32_e32 v107, 1.0, v107
	v_rcp_f32_e32 v104, v104
	v_rcp_f32_e32 v105, v105
	v_rcp_f32_e32 v106, v106
	v_rcp_f32_e32 v107, v107
	v_or_b32_e32 v122, 0x100, v114
	v_mov_b32_e32 v123, v115
	v_mul_f32_e32 v102, v102, v143
	v_mul_f32_e32 v103, v103, v143
	v_mul_f32_e32 v100, v100, v143
	v_mul_f32_e32 v101, v101, v143
	v_mul_f32_e32 v102, 0xbfb8aa3b, v102
	v_mul_f32_e32 v103, 0xbfb8aa3b, v103
	v_mul_f32_e32 v100, 0xbfb8aa3b, v100
	v_mul_f32_e32 v101, 0xbfb8aa3b, v101
	v_exp_f32_e32 v102, v102
	v_exp_f32_e32 v103, v103
	v_exp_f32_e32 v100, v100
	v_exp_f32_e32 v101, v101
	v_add_f32_e32 v102, 1.0, v102
	v_add_f32_e32 v103, 1.0, v103
	v_add_f32_e32 v100, 1.0, v100
	v_add_f32_e32 v101, 1.0, v101
	v_rcp_f32_e32 v102, v102
	v_rcp_f32_e32 v103, v103
	v_rcp_f32_e32 v100, v100
	v_rcp_f32_e32 v101, v101
	v_or_b32_e32 v114, 0x120, v114
	v_mul_f32_e32 v96, v96, v143
	v_mul_f32_e32 v97, v97, v143
	v_mul_f32_e32 v98, v98, v143
	v_mul_f32_e32 v99, v99, v143
	v_mul_f32_e32 v96, 0xbfb8aa3b, v96
	v_mul_f32_e32 v97, 0xbfb8aa3b, v97
	v_mul_f32_e32 v98, 0xbfb8aa3b, v98
	v_mul_f32_e32 v99, 0xbfb8aa3b, v99
	v_exp_f32_e32 v96, v96
	v_exp_f32_e32 v97, v97
	v_exp_f32_e32 v98, v98
	v_exp_f32_e32 v99, v99
	v_add_f32_e32 v96, 1.0, v96
	v_add_f32_e32 v97, 1.0, v97
	v_add_f32_e32 v98, 1.0, v98
	v_add_f32_e32 v99, 1.0, v99
	v_mul_f32_e32 v111, v111, v111
	v_mul_f32_e32 v109, v109, v109
	v_rcp_f32_e32 v96, v96
	v_rcp_f32_e32 v97, v97
	v_rcp_f32_e32 v98, v98
	v_rcp_f32_e32 v99, v99
	v_fmac_f32_e32 v111, v110, v110
	v_fmac_f32_e32 v109, v108, v108
	v_add_f32_e32 v108, v111, v109
	s_waitcnt vmcnt(0)
	v_lshlrev_b32_e32 v124, 16, v210
	v_and_b32_e32 v125, 0xffff0000, v210
	s_waitcnt vmcnt(0)
	v_lshlrev_b32_e32 v126, 16, v202
	v_and_b32_e32 v127, 0xffff0000, v202
	v_lshlrev_b32_e32 v120, 16, v211
	v_and_b32_e32 v121, 0xffff0000, v211
	v_lshlrev_b32_e32 v118, 16, v203
	v_and_b32_e32 v119, 0xffff0000, v203
	v_pk_fma_f32 v[104:105], v[104:105], v[126:127], v[124:125]
	v_lshl_add_u64 v[124:125], s[16:17], 0, v[164:165]
	v_pk_fma_f32 v[106:107], v[106:107], v[118:119], v[120:121]
	v_cvt_pk_bf16_f32 v118, v104, v105
	v_lshl_add_u64 v[126:127], s[20:21], 0, v[122:123]
	v_cvt_pk_bf16_f32 v119, v106, v107
	v_mov_b32_e32 v222, v118
	v_mov_b32_e32 v223, v119
	v_bfe_u32 v228, v206, 4, 1
	v_mul_u32_u24_e32 v228, 24, v228
	v_mov_b32_e32 v229, 0
	v_lshl_add_u64 v[230:231], v[124:125], 0, v[228:229]
	v_permlane16_swap_b32_e32 v220, v222
	v_permlane16_swap_b32_e32 v221, v223
	global_store_dwordx4 v[230:231], v[220:223], off offset:-32
	v_bfe_u32 v228, v206, 4, 1
	v_mul_u32_u24_e32 v228, 24, v228
	v_mov_b32_e32 v229, 0
	v_lshl_add_u64 v[230:231], v[116:117], 0, v[228:229]
	global_load_dwordx4 v[212:215], v[230:231], off offset:256
	v_mul_f32_e32 v105, v105, v105
	v_bfe_u32 v228, v206, 4, 1
	v_mul_u32_u24_e32 v228, 24, v228
	v_mov_b32_e32 v229, 0
	v_lshl_add_u64 v[230:231], v[126:127], 0, v[228:229]
	global_load_dwordx4 v[216:219], v[230:231], off
	v_mul_f32_e32 v107, v107, v107
	v_fmac_f32_e32 v105, v104, v104
	v_fmac_f32_e32 v107, v106, v106
	v_add_f32_e32 v104, v105, v107
	v_add_f32_e32 v104, v108, v104
	s_waitcnt vmcnt(0)
	v_permlane16_swap_b32_e32 v212, v214
	v_permlane16_swap_b32_e32 v213, v215
	v_permlane16_swap_b32_e32 v216, v218
	v_permlane16_swap_b32_e32 v217, v219
	v_lshlrev_b32_e32 v124, 16, v212
	v_and_b32_e32 v125, 0xffff0000, v212
	v_lshlrev_b32_e32 v120, 16, v213
	v_and_b32_e32 v121, 0xffff0000, v213
	s_waitcnt vmcnt(0)
	v_lshlrev_b32_e32 v126, 16, v216
	v_and_b32_e32 v127, 0xffff0000, v216
	v_lshlrev_b32_e32 v118, 16, v217
	v_and_b32_e32 v119, 0xffff0000, v217
	v_pk_fma_f32 v[102:103], v[102:103], v[118:119], v[120:121]
	v_lshl_add_u64 v[120:121], s[16:17], 0, v[122:123]
	v_pk_fma_f32 v[100:101], v[100:101], v[126:127], v[124:125]
	v_lshl_add_u64 v[122:123], s[20:21], 0, v[114:115]
	v_cvt_pk_bf16_f32 v118, v100, v101
	v_cvt_pk_bf16_f32 v119, v102, v103
	v_mov_b32_e32 v224, v118
	v_mov_b32_e32 v225, v119
	v_mul_f32_e32 v101, v101, v101
	v_mul_f32_e32 v103, v103, v103
	v_fmac_f32_e32 v101, v100, v100
	v_fmac_f32_e32 v103, v102, v102
	v_add_f32_e32 v100, v101, v103
	v_add_f32_e32 v108, v100, v104
	s_waitcnt vmcnt(0)
	v_lshlrev_b32_e32 v100, 16, v214
	v_and_b32_e32 v101, 0xffff0000, v214
	v_lshlrev_b32_e32 v102, 16, v215
	v_and_b32_e32 v103, 0xffff0000, v215
	s_waitcnt vmcnt(0)
	v_lshlrev_b32_e32 v104, 16, v218
	v_and_b32_e32 v105, 0xffff0000, v218
	v_lshlrev_b32_e32 v106, 16, v219
	v_and_b32_e32 v107, 0xffff0000, v219
	v_pk_fma_f32 v[98:99], v[98:99], v[106:107], v[102:103]
	v_pk_fma_f32 v[96:97], v[96:97], v[104:105], v[100:101]
	v_mul_f32_e32 v101, v99, v99
	v_mul_f32_e32 v100, v97, v97
	v_fmac_f32_e32 v100, v96, v96
	v_fmac_f32_e32 v101, v98, v98
	v_add_f32_e32 v100, v100, v101
	v_add_f32_e32 v102, v108, v100
	ds_swizzle_b32 v103, v102 offset:swizzle(SWAP,16)
	v_lshl_add_u64 v[100:101], s[16:17], 0, v[114:115]
	v_cvt_pk_bf16_f32 v96, v96, v97
	v_cvt_pk_bf16_f32 v97, v98, v99
	v_mov_b32_e32 v226, v96
	v_mov_b32_e32 v227, v97
	v_bfe_u32 v228, v206, 4, 1
	v_mul_u32_u24_e32 v228, 24, v228
	v_mov_b32_e32 v229, 0
	v_lshl_add_u64 v[230:231], v[100:101], 0, v[228:229]
	v_permlane16_swap_b32_e32 v224, v226
	v_permlane16_swap_b32_e32 v225, v227
	global_store_dwordx4 v[230:231], v[224:227], off offset:-32
	s_waitcnt lgkmcnt(0)
	v_add_f32_e32 v96, v102, v103
	v_mov_b32_e32 v97, v96
	s_nop 1
	v_permlane32_swap_b32_e32 v96, v97
	s_and_saveexec_b64 s[2:3], s[4:5]
	s_cbranch_execz .LBB0_902
	v_add_f32_e32 v98, v96, v97
	v_lshl_add_u64 v[96:97], s[18:19], 0, v[112:113]
	v_lshl_add_u64 v[96:97], s[36:37], 2, v[96:97]
	s_lshl_b32 s12, s50, 2
	v_lshl_add_u64 v[96:97], v[96:97], 0, s[12:13]
	global_store_dword v[96:97], v98, off
.LBB0_902:
	s_or_b64 exec, exec, s[2:3]
	v_or_b32_e32 v98, 32, v142
	v_ashrrev_i32_e32 v99, 31, v98
	v_lshlrev_b64 v[96:97], 6, v[98:99]
	v_lshl_add_u64 v[100:101], s[10:11], 0, v[96:97]
	v_bfe_u32 v110, v206, 4, 2
	v_lshlrev_b32_e32 v110, 4, v110
	v_mov_b32_e32 v111, 0
	v_lshl_add_u64 v[106:107], v[100:101], 0, v[110:111]
	global_load_dwordx4 v[102:105], v[106:107], off
	v_lshlrev_b64 v[98:99], 10, v[98:99]
	v_lshl_add_u64 v[98:99], v[98:99], 0, v[140:141]
	v_lshlrev_b64 v[98:99], 1, v[98:99]
	v_lshl_add_u64 v[100:101], s[20:21], 0, v[98:99]
	v_bfe_u32 v228, v206, 4, 1
	v_mul_u32_u24_e32 v228, 24, v228
	v_mov_b32_e32 v229, 0
	v_lshl_add_u64 v[230:231], v[100:101], 0, v[228:229]
	global_load_dwordx4 v[184:187], v[230:231], off
	v_lshl_add_u64 v[100:101], s[8:9], 0, v[98:99]
	v_bfe_u32 v228, v206, 4, 1
	v_mul_u32_u24_e32 v228, 24, v228
	v_mov_b32_e32 v229, 0
	v_lshl_add_u64 v[230:231], v[100:101], 0, v[228:229]
	global_load_dwordx4 v[188:191], v[230:231], off
	v_lshl_add_u64 v[122:123], s[16:17], 0, v[98:99]
	v_or_b32_e32 v124, 32, v98
	v_mov_b32_e32 v125, v99
	s_waitcnt vmcnt(0)
	v_permlane16_swap_b32_e32 v184, v186
	v_permlane16_swap_b32_e32 v185, v187
	v_permlane16_swap_b32_e32 v188, v190
	v_permlane16_swap_b32_e32 v189, v191
	v_add_f32_e32 v106, v102, v103
	v_add_f32_e32 v107, v104, v105
	v_add_f32_e32 v106, v106, v107
	ds_swizzle_b32 v107, v106 offset:swizzle(SWAP,16)
	s_waitcnt lgkmcnt(0)
	v_add_f32_e32 v106, v106, v107
	v_mov_b32_e32 v107, v106
	s_nop 1
	v_permlane32_swap_b32_e32 v106, v107
	v_add_f32_e32 v114, v106, v107
	v_lshlrev_b32_e32 v108, 16, v185
	v_lshlrev_b32_e32 v104, 16, v184
	v_mov_b32_e32 v102, v114
	v_fmamk_f32 v102, v102, 0x3a800000, v156
	v_mul_f32_e32 v103, 0x4b800000, v102
	v_cmp_gt_f32_e32 vcc, s56, v102
	v_and_b32_e32 v105, 0xffff0000, v184
	v_and_b32_e32 v109, 0xffff0000, v185
	v_cndmask_b32_e32 v102, v102, v103, vcc
	v_rsq_f32_e32 v106, v102
	s_waitcnt vmcnt(0)
	v_lshlrev_b32_e32 v102, 16, v188
	v_and_b32_e32 v103, 0xffff0000, v188
	v_mul_f32_e32 v107, 0x45800000, v106
	v_cndmask_b32_e32 v112, v106, v107, vcc
	v_mul_f32_e32 v92, v92, v112
	v_mul_f32_e32 v93, v93, v112
	v_mul_f32_e32 v94, v94, v112
	v_mul_f32_e32 v95, v95, v112
	v_mul_f32_e32 v92, 0xbfb8aa3b, v92
	v_mul_f32_e32 v93, 0xbfb8aa3b, v93
	v_mul_f32_e32 v94, 0xbfb8aa3b, v94
	v_mul_f32_e32 v95, 0xbfb8aa3b, v95
	v_exp_f32_e32 v92, v92
	v_exp_f32_e32 v93, v93
	v_exp_f32_e32 v94, v94
	v_exp_f32_e32 v95, v95
	v_add_f32_e32 v92, 1.0, v92
	v_add_f32_e32 v106, 1.0, v93
	v_add_f32_e32 v93, 1.0, v94
	v_add_f32_e32 v95, 1.0, v95
	v_rcp_f32_e32 v94, v92
	v_rcp_f32_e32 v92, v93
	v_rcp_f32_e32 v93, v95
	v_rcp_f32_e32 v95, v106
	v_lshlrev_b32_e32 v106, 16, v189
	v_and_b32_e32 v107, 0xffff0000, v189
	v_pk_fma_f32 v[92:93], v[92:93], v[108:109], v[106:107]
	v_pk_fma_f32 v[94:95], v[94:95], v[104:105], v[102:103]
	v_lshl_add_u64 v[106:107], s[20:21], 0, v[124:125]
	v_cvt_pk_bf16_f32 v102, v94, v95
	v_cvt_pk_bf16_f32 v103, v92, v93
	v_mov_b32_e32 v220, v102
	v_mov_b32_e32 v221, v103
	v_mul_f32_e32 v88, v88, v112
	v_mul_f32_e32 v89, v89, v112
	v_mul_f32_e32 v90, v90, v112
	v_mul_f32_e32 v91, v91, v112
	v_mul_f32_e32 v88, 0xbfb8aa3b, v88
	v_mul_f32_e32 v89, 0xbfb8aa3b, v89
	v_mul_f32_e32 v90, 0xbfb8aa3b, v90
	v_mul_f32_e32 v91, 0xbfb8aa3b, v91
	v_exp_f32_e32 v88, v88
	v_exp_f32_e32 v89, v89
	v_exp_f32_e32 v90, v90
	v_exp_f32_e32 v91, v91
	v_add_f32_e32 v88, 1.0, v88
	v_add_f32_e32 v89, 1.0, v89
	v_add_f32_e32 v90, 1.0, v90
	v_add_f32_e32 v91, 1.0, v91
	v_rcp_f32_e32 v88, v88
	v_rcp_f32_e32 v89, v89
	v_rcp_f32_e32 v90, v90
	v_rcp_f32_e32 v91, v91
	v_or_b32_e32 v106, 0x100, v98
	v_mov_b32_e32 v107, v99
	v_mul_f32_e32 v86, v86, v112
	v_mul_f32_e32 v87, v87, v112
	v_mul_f32_e32 v84, v84, v112
	v_mul_f32_e32 v85, v85, v112
	v_mul_f32_e32 v86, 0xbfb8aa3b, v86
	v_mul_f32_e32 v87, 0xbfb8aa3b, v87
	v_mul_f32_e32 v84, 0xbfb8aa3b, v84
	v_mul_f32_e32 v85, 0xbfb8aa3b, v85
	v_exp_f32_e32 v86, v86
	v_exp_f32_e32 v87, v87
	v_exp_f32_e32 v84, v84
	v_exp_f32_e32 v85, v85
	v_add_f32_e32 v86, 1.0, v86
	v_add_f32_e32 v87, 1.0, v87
	v_add_f32_e32 v84, 1.0, v84
	v_add_f32_e32 v85, 1.0, v85
	v_rcp_f32_e32 v86, v86
	v_rcp_f32_e32 v87, v87
	v_rcp_f32_e32 v84, v84
	v_rcp_f32_e32 v85, v85
	v_or_b32_e32 v98, 0x120, v98
	v_mul_f32_e32 v80, v80, v112
	v_mul_f32_e32 v81, v81, v112
	v_mul_f32_e32 v82, v82, v112
	v_mul_f32_e32 v83, v83, v112
	v_mul_f32_e32 v80, 0xbfb8aa3b, v80
	v_mul_f32_e32 v81, 0xbfb8aa3b, v81
	v_mul_f32_e32 v82, 0xbfb8aa3b, v82
	v_mul_f32_e32 v83, 0xbfb8aa3b, v83
	v_exp_f32_e32 v80, v80
	v_exp_f32_e32 v81, v81
	v_exp_f32_e32 v82, v82
	v_exp_f32_e32 v83, v83
	v_add_f32_e32 v80, 1.0, v80
	v_add_f32_e32 v81, 1.0, v81
	v_add_f32_e32 v82, 1.0, v82
	v_add_f32_e32 v83, 1.0, v83
	v_mul_f32_e32 v95, v95, v95
	v_mul_f32_e32 v93, v93, v93
	v_rcp_f32_e32 v80, v80
	v_rcp_f32_e32 v81, v81
	v_rcp_f32_e32 v82, v82
	v_rcp_f32_e32 v83, v83
	v_fmac_f32_e32 v95, v94, v94
	v_fmac_f32_e32 v93, v92, v92
	v_add_f32_e32 v92, v95, v93
	s_waitcnt vmcnt(0)
	v_lshlrev_b32_e32 v108, 16, v190
	v_and_b32_e32 v109, 0xffff0000, v190
	s_waitcnt vmcnt(0)
	v_lshlrev_b32_e32 v110, 16, v186
	v_and_b32_e32 v111, 0xffff0000, v186
	v_lshlrev_b32_e32 v104, 16, v191
	v_and_b32_e32 v105, 0xffff0000, v191
	v_lshlrev_b32_e32 v102, 16, v187
	v_and_b32_e32 v103, 0xffff0000, v187
	v_pk_fma_f32 v[88:89], v[88:89], v[110:111], v[108:109]
	v_lshl_add_u64 v[108:109], s[16:17], 0, v[124:125]
	v_pk_fma_f32 v[90:91], v[90:91], v[102:103], v[104:105]
	v_cvt_pk_bf16_f32 v102, v88, v89
	v_lshl_add_u64 v[110:111], s[20:21], 0, v[106:107]
	v_cvt_pk_bf16_f32 v103, v90, v91
	v_mov_b32_e32 v222, v102
	v_mov_b32_e32 v223, v103
	v_bfe_u32 v228, v206, 4, 1
	v_mul_u32_u24_e32 v228, 24, v228
	v_mov_b32_e32 v229, 0
	v_lshl_add_u64 v[230:231], v[108:109], 0, v[228:229]
	v_permlane16_swap_b32_e32 v220, v222
	v_permlane16_swap_b32_e32 v221, v223
	global_store_dwordx4 v[230:231], v[220:223], off offset:-32
	v_bfe_u32 v228, v206, 4, 1
	v_mul_u32_u24_e32 v228, 24, v228
	v_mov_b32_e32 v229, 0
	v_lshl_add_u64 v[230:231], v[100:101], 0, v[228:229]
	global_load_dwordx4 v[192:195], v[230:231], off offset:256
	v_mul_f32_e32 v89, v89, v89
	v_bfe_u32 v228, v206, 4, 1
	v_mul_u32_u24_e32 v228, 24, v228
	v_mov_b32_e32 v229, 0
	v_lshl_add_u64 v[230:231], v[110:111], 0, v[228:229]
	global_load_dwordx4 v[196:199], v[230:231], off
	v_mul_f32_e32 v91, v91, v91
	v_fmac_f32_e32 v89, v88, v88
	v_fmac_f32_e32 v91, v90, v90
	v_add_f32_e32 v88, v89, v91
	v_add_f32_e32 v88, v92, v88
	s_waitcnt vmcnt(0)
	v_permlane16_swap_b32_e32 v192, v194
	v_permlane16_swap_b32_e32 v193, v195
	v_permlane16_swap_b32_e32 v196, v198
	v_permlane16_swap_b32_e32 v197, v199
	v_lshlrev_b32_e32 v108, 16, v192
	v_and_b32_e32 v109, 0xffff0000, v192
	v_lshlrev_b32_e32 v104, 16, v193
	v_and_b32_e32 v105, 0xffff0000, v193
	s_waitcnt vmcnt(0)
	v_lshlrev_b32_e32 v110, 16, v196
	v_and_b32_e32 v111, 0xffff0000, v196
	v_lshlrev_b32_e32 v102, 16, v197
	v_and_b32_e32 v103, 0xffff0000, v197
	v_pk_fma_f32 v[86:87], v[86:87], v[102:103], v[104:105]
	v_lshl_add_u64 v[104:105], s[16:17], 0, v[106:107]
	v_pk_fma_f32 v[84:85], v[84:85], v[110:111], v[108:109]
	v_lshl_add_u64 v[106:107], s[20:21], 0, v[98:99]
	v_cvt_pk_bf16_f32 v102, v84, v85
	v_cvt_pk_bf16_f32 v103, v86, v87
	v_mov_b32_e32 v224, v102
	v_mov_b32_e32 v225, v103
	v_mul_f32_e32 v85, v85, v85
	v_mul_f32_e32 v87, v87, v87
	v_fmac_f32_e32 v85, v84, v84
	v_fmac_f32_e32 v87, v86, v86
	v_add_f32_e32 v84, v85, v87
	v_add_f32_e32 v92, v84, v88
	s_waitcnt vmcnt(0)
	v_lshlrev_b32_e32 v84, 16, v194
	v_and_b32_e32 v85, 0xffff0000, v194
	v_lshlrev_b32_e32 v86, 16, v195
	v_and_b32_e32 v87, 0xffff0000, v195
	s_waitcnt vmcnt(0)
	v_lshlrev_b32_e32 v88, 16, v198
	v_and_b32_e32 v89, 0xffff0000, v198
	v_lshlrev_b32_e32 v90, 16, v199
	v_and_b32_e32 v91, 0xffff0000, v199
	v_pk_fma_f32 v[82:83], v[82:83], v[90:91], v[86:87]
	v_pk_fma_f32 v[80:81], v[80:81], v[88:89], v[84:85]
	v_mul_f32_e32 v85, v83, v83
	v_mul_f32_e32 v84, v81, v81
	v_fmac_f32_e32 v84, v80, v80
	v_fmac_f32_e32 v85, v82, v82
	v_add_f32_e32 v84, v84, v85
	v_add_f32_e32 v86, v92, v84
	ds_swizzle_b32 v87, v86 offset:swizzle(SWAP,16)
	v_lshl_add_u64 v[84:85], s[16:17], 0, v[98:99]
	v_cvt_pk_bf16_f32 v80, v80, v81
	v_cvt_pk_bf16_f32 v81, v82, v83
	v_mov_b32_e32 v226, v80
	v_mov_b32_e32 v227, v81
	v_bfe_u32 v228, v206, 4, 1
	v_mul_u32_u24_e32 v228, 24, v228
	v_mov_b32_e32 v229, 0
	v_lshl_add_u64 v[230:231], v[84:85], 0, v[228:229]
	v_permlane16_swap_b32_e32 v224, v226
	v_permlane16_swap_b32_e32 v225, v227
	global_store_dwordx4 v[230:231], v[224:227], off offset:-32
	s_waitcnt lgkmcnt(0)
	v_add_f32_e32 v80, v86, v87
	v_mov_b32_e32 v81, v80
	s_nop 1
	v_permlane32_swap_b32_e32 v80, v81
	s_and_saveexec_b64 s[2:3], s[4:5]
	s_cbranch_execz .LBB0_904
	v_add_f32_e32 v82, v80, v81
	v_lshl_add_u64 v[80:81], s[18:19], 0, v[96:97]
	v_lshl_add_u64 v[80:81], s[36:37], 2, v[80:81]
	s_lshl_b32 s12, s50, 2
	v_lshl_add_u64 v[80:81], v[80:81], 0, s[12:13]
	global_store_dword v[80:81], v82, off
.LBB0_904:
	s_or_b64 exec, exec, s[2:3]
	v_or_b32_e32 v82, 48, v142
	v_ashrrev_i32_e32 v83, 31, v82
	v_lshlrev_b64 v[80:81], 6, v[82:83]
	v_lshl_add_u64 v[84:85], s[10:11], 0, v[80:81]
	v_bfe_u32 v94, v206, 4, 2
	v_lshlrev_b32_e32 v94, 4, v94
	v_mov_b32_e32 v95, 0
	v_lshl_add_u64 v[90:91], v[84:85], 0, v[94:95]
	global_load_dwordx4 v[86:89], v[90:91], off
	v_lshlrev_b64 v[82:83], 10, v[82:83]
	v_lshl_add_u64 v[82:83], v[82:83], 0, v[140:141]
	v_lshlrev_b64 v[82:83], 1, v[82:83]
	v_lshl_add_u64 v[84:85], s[20:21], 0, v[82:83]
	v_bfe_u32 v228, v206, 4, 1
	v_mul_u32_u24_e32 v228, 24, v228
	v_mov_b32_e32 v229, 0
	v_lshl_add_u64 v[230:231], v[84:85], 0, v[228:229]
	global_load_dwordx4 v[200:203], v[230:231], off
	v_lshl_add_u64 v[84:85], s[8:9], 0, v[82:83]
	v_bfe_u32 v228, v206, 4, 1
	v_mul_u32_u24_e32 v228, 24, v228
	v_mov_b32_e32 v229, 0
	v_lshl_add_u64 v[230:231], v[84:85], 0, v[228:229]
	global_load_dwordx4 v[208:211], v[230:231], off
	v_lshl_add_u64 v[106:107], s[16:17], 0, v[82:83]
	v_or_b32_e32 v108, 32, v82
	v_mov_b32_e32 v109, v83
	s_waitcnt vmcnt(0)
	v_permlane16_swap_b32_e32 v200, v202
	v_permlane16_swap_b32_e32 v201, v203
	v_permlane16_swap_b32_e32 v208, v210
	v_permlane16_swap_b32_e32 v209, v211
	v_add_f32_e32 v90, v86, v87
	v_add_f32_e32 v91, v88, v89
	v_add_f32_e32 v90, v90, v91
	ds_swizzle_b32 v91, v90 offset:swizzle(SWAP,16)
	s_waitcnt lgkmcnt(0)
	v_add_f32_e32 v90, v90, v91
	v_mov_b32_e32 v91, v90
	s_nop 1
	v_permlane32_swap_b32_e32 v90, v91
	v_add_f32_e32 v98, v90, v91
	v_lshlrev_b32_e32 v92, 16, v201
	v_lshlrev_b32_e32 v88, 16, v200
	v_mov_b32_e32 v86, v98
	v_fmamk_f32 v86, v86, 0x3a800000, v156
	v_mul_f32_e32 v87, 0x4b800000, v86
	v_cmp_gt_f32_e32 vcc, s56, v86
	v_and_b32_e32 v89, 0xffff0000, v200
	v_and_b32_e32 v93, 0xffff0000, v201
	v_cndmask_b32_e32 v86, v86, v87, vcc
	v_rsq_f32_e32 v90, v86
	s_waitcnt vmcnt(0)
	v_lshlrev_b32_e32 v86, 16, v208
	v_and_b32_e32 v87, 0xffff0000, v208
	v_mul_f32_e32 v91, 0x45800000, v90
	v_cndmask_b32_e32 v96, v90, v91, vcc
	v_mul_f32_e32 v76, v76, v96
	v_mul_f32_e32 v77, v77, v96
	v_mul_f32_e32 v78, v78, v96
	v_mul_f32_e32 v79, v79, v96
	v_mul_f32_e32 v76, 0xbfb8aa3b, v76
	v_mul_f32_e32 v77, 0xbfb8aa3b, v77
	v_mul_f32_e32 v78, 0xbfb8aa3b, v78
	v_mul_f32_e32 v79, 0xbfb8aa3b, v79
	v_exp_f32_e32 v76, v76
	v_exp_f32_e32 v77, v77
	v_exp_f32_e32 v78, v78
	v_exp_f32_e32 v79, v79
	v_add_f32_e32 v76, 1.0, v76
	v_add_f32_e32 v90, 1.0, v77
	v_add_f32_e32 v77, 1.0, v78
	v_add_f32_e32 v79, 1.0, v79
	v_rcp_f32_e32 v78, v76
	v_rcp_f32_e32 v76, v77
	v_rcp_f32_e32 v77, v79
	v_rcp_f32_e32 v79, v90
	v_lshlrev_b32_e32 v90, 16, v209
	v_and_b32_e32 v91, 0xffff0000, v209
	v_pk_fma_f32 v[76:77], v[76:77], v[92:93], v[90:91]
	v_pk_fma_f32 v[78:79], v[78:79], v[88:89], v[86:87]
	v_lshl_add_u64 v[90:91], s[20:21], 0, v[108:109]
	v_cvt_pk_bf16_f32 v86, v78, v79
	v_cvt_pk_bf16_f32 v87, v76, v77
	v_mov_b32_e32 v220, v86
	v_mov_b32_e32 v221, v87
	v_mul_f32_e32 v72, v72, v96
	v_mul_f32_e32 v73, v73, v96
	v_mul_f32_e32 v74, v74, v96
	v_mul_f32_e32 v75, v75, v96
	v_mul_f32_e32 v72, 0xbfb8aa3b, v72
	v_mul_f32_e32 v73, 0xbfb8aa3b, v73
	v_mul_f32_e32 v74, 0xbfb8aa3b, v74
	v_mul_f32_e32 v75, 0xbfb8aa3b, v75
	v_exp_f32_e32 v72, v72
	v_exp_f32_e32 v73, v73
	v_exp_f32_e32 v74, v74
	v_exp_f32_e32 v75, v75
	v_add_f32_e32 v72, 1.0, v72
	v_add_f32_e32 v73, 1.0, v73
	v_add_f32_e32 v74, 1.0, v74
	v_add_f32_e32 v75, 1.0, v75
	v_rcp_f32_e32 v72, v72
	v_rcp_f32_e32 v73, v73
	v_rcp_f32_e32 v74, v74
	v_rcp_f32_e32 v75, v75
	v_or_b32_e32 v90, 0x100, v82
	v_mov_b32_e32 v91, v83
	v_mul_f32_e32 v70, v70, v96
	v_mul_f32_e32 v71, v71, v96
	v_mul_f32_e32 v68, v68, v96
	v_mul_f32_e32 v69, v69, v96
	v_mul_f32_e32 v70, 0xbfb8aa3b, v70
	v_mul_f32_e32 v71, 0xbfb8aa3b, v71
	v_mul_f32_e32 v68, 0xbfb8aa3b, v68
	v_mul_f32_e32 v69, 0xbfb8aa3b, v69
	v_exp_f32_e32 v70, v70
	v_exp_f32_e32 v71, v71
	v_exp_f32_e32 v68, v68
	v_exp_f32_e32 v69, v69
	v_add_f32_e32 v70, 1.0, v70
	v_add_f32_e32 v71, 1.0, v71
	v_add_f32_e32 v68, 1.0, v68
	v_add_f32_e32 v69, 1.0, v69
	v_rcp_f32_e32 v70, v70
	v_rcp_f32_e32 v71, v71
	v_rcp_f32_e32 v68, v68
	v_rcp_f32_e32 v69, v69
	v_or_b32_e32 v82, 0x120, v82
	v_mul_f32_e32 v64, v64, v96
	v_mul_f32_e32 v65, v65, v96
	v_mul_f32_e32 v66, v66, v96
	v_mul_f32_e32 v67, v67, v96
	v_mul_f32_e32 v64, 0xbfb8aa3b, v64
	v_mul_f32_e32 v65, 0xbfb8aa3b, v65
	v_mul_f32_e32 v66, 0xbfb8aa3b, v66
	v_mul_f32_e32 v67, 0xbfb8aa3b, v67
	v_exp_f32_e32 v64, v64
	v_exp_f32_e32 v65, v65
	v_exp_f32_e32 v66, v66
	v_exp_f32_e32 v67, v67
	v_add_f32_e32 v64, 1.0, v64
	v_add_f32_e32 v65, 1.0, v65
	v_add_f32_e32 v66, 1.0, v66
	v_add_f32_e32 v67, 1.0, v67
	v_mul_f32_e32 v79, v79, v79
	v_mul_f32_e32 v77, v77, v77
	v_rcp_f32_e32 v64, v64
	v_rcp_f32_e32 v65, v65
	v_rcp_f32_e32 v66, v66
	v_rcp_f32_e32 v67, v67
	v_fmac_f32_e32 v79, v78, v78
	v_fmac_f32_e32 v77, v76, v76
	v_add_f32_e32 v76, v79, v77
	s_waitcnt vmcnt(0)
	v_lshlrev_b32_e32 v92, 16, v210
	v_and_b32_e32 v93, 0xffff0000, v210
	s_waitcnt vmcnt(0)
	v_lshlrev_b32_e32 v94, 16, v202
	v_and_b32_e32 v95, 0xffff0000, v202
	v_lshlrev_b32_e32 v88, 16, v211
	v_and_b32_e32 v89, 0xffff0000, v211
	v_lshlrev_b32_e32 v86, 16, v203
	v_and_b32_e32 v87, 0xffff0000, v203
	v_pk_fma_f32 v[72:73], v[72:73], v[94:95], v[92:93]
	v_lshl_add_u64 v[92:93], s[16:17], 0, v[108:109]
	v_pk_fma_f32 v[74:75], v[74:75], v[86:87], v[88:89]
	v_cvt_pk_bf16_f32 v86, v72, v73
	v_lshl_add_u64 v[94:95], s[20:21], 0, v[90:91]
	v_cvt_pk_bf16_f32 v87, v74, v75
	v_mov_b32_e32 v222, v86
	v_mov_b32_e32 v223, v87
	v_bfe_u32 v228, v206, 4, 1
	v_mul_u32_u24_e32 v228, 24, v228
	v_mov_b32_e32 v229, 0
	v_lshl_add_u64 v[230:231], v[92:93], 0, v[228:229]
	v_permlane16_swap_b32_e32 v220, v222
	v_permlane16_swap_b32_e32 v221, v223
	global_store_dwordx4 v[230:231], v[220:223], off offset:-32
	v_bfe_u32 v228, v206, 4, 1
	v_mul_u32_u24_e32 v228, 24, v228
	v_mov_b32_e32 v229, 0
	v_lshl_add_u64 v[230:231], v[84:85], 0, v[228:229]
	global_load_dwordx4 v[212:215], v[230:231], off offset:256
	v_mul_f32_e32 v73, v73, v73
	v_bfe_u32 v228, v206, 4, 1
	v_mul_u32_u24_e32 v228, 24, v228
	v_mov_b32_e32 v229, 0
	v_lshl_add_u64 v[230:231], v[94:95], 0, v[228:229]
	global_load_dwordx4 v[216:219], v[230:231], off
	v_mul_f32_e32 v75, v75, v75
	v_fmac_f32_e32 v73, v72, v72
	v_fmac_f32_e32 v75, v74, v74
	v_add_f32_e32 v72, v73, v75
	v_add_f32_e32 v72, v76, v72
	s_waitcnt vmcnt(0)
	v_permlane16_swap_b32_e32 v212, v214
	v_permlane16_swap_b32_e32 v213, v215
	v_permlane16_swap_b32_e32 v216, v218
	v_permlane16_swap_b32_e32 v217, v219
	v_lshlrev_b32_e32 v92, 16, v212
	v_and_b32_e32 v93, 0xffff0000, v212
	v_lshlrev_b32_e32 v88, 16, v213
	v_and_b32_e32 v89, 0xffff0000, v213
	s_waitcnt vmcnt(0)
	v_lshlrev_b32_e32 v94, 16, v216
	v_and_b32_e32 v95, 0xffff0000, v216
	v_lshlrev_b32_e32 v86, 16, v217
	v_and_b32_e32 v87, 0xffff0000, v217
	v_pk_fma_f32 v[70:71], v[70:71], v[86:87], v[88:89]
	v_lshl_add_u64 v[88:89], s[16:17], 0, v[90:91]
	v_pk_fma_f32 v[68:69], v[68:69], v[94:95], v[92:93]
	v_lshl_add_u64 v[90:91], s[20:21], 0, v[82:83]
	v_cvt_pk_bf16_f32 v86, v68, v69
	v_cvt_pk_bf16_f32 v87, v70, v71
	v_mov_b32_e32 v224, v86
	v_mov_b32_e32 v225, v87
	v_mul_f32_e32 v69, v69, v69
	v_mul_f32_e32 v71, v71, v71
	v_fmac_f32_e32 v69, v68, v68
	v_fmac_f32_e32 v71, v70, v70
	v_add_f32_e32 v68, v69, v71
	v_add_f32_e32 v76, v68, v72
	s_waitcnt vmcnt(0)
	v_lshlrev_b32_e32 v68, 16, v214
	v_and_b32_e32 v69, 0xffff0000, v214
	v_lshlrev_b32_e32 v70, 16, v215
	v_and_b32_e32 v71, 0xffff0000, v215
	s_waitcnt vmcnt(0)
	v_lshlrev_b32_e32 v72, 16, v218
	v_and_b32_e32 v73, 0xffff0000, v218
	v_lshlrev_b32_e32 v74, 16, v219
	v_and_b32_e32 v75, 0xffff0000, v219
	v_pk_fma_f32 v[66:67], v[66:67], v[74:75], v[70:71]
	v_pk_fma_f32 v[64:65], v[64:65], v[72:73], v[68:69]
	v_mul_f32_e32 v69, v67, v67
	v_mul_f32_e32 v68, v65, v65
	v_fmac_f32_e32 v68, v64, v64
	v_fmac_f32_e32 v69, v66, v66
	v_add_f32_e32 v68, v68, v69
	v_add_f32_e32 v70, v76, v68
	ds_swizzle_b32 v71, v70 offset:swizzle(SWAP,16)
	v_lshl_add_u64 v[68:69], s[16:17], 0, v[82:83]
	v_cvt_pk_bf16_f32 v64, v64, v65
	v_cvt_pk_bf16_f32 v65, v66, v67
	v_mov_b32_e32 v226, v64
	v_mov_b32_e32 v227, v65
	v_bfe_u32 v228, v206, 4, 1
	v_mul_u32_u24_e32 v228, 24, v228
	v_mov_b32_e32 v229, 0
	v_lshl_add_u64 v[230:231], v[68:69], 0, v[228:229]
	v_permlane16_swap_b32_e32 v224, v226
	v_permlane16_swap_b32_e32 v225, v227
	global_store_dwordx4 v[230:231], v[224:227], off offset:-32
	s_waitcnt lgkmcnt(0)
	v_add_f32_e32 v64, v70, v71
	v_mov_b32_e32 v65, v64
	s_nop 1
	v_permlane32_swap_b32_e32 v64, v65
	s_and_saveexec_b64 s[2:3], s[4:5]
	s_cbranch_execz .LBB0_906
	v_add_f32_e32 v66, v64, v65
	v_lshl_add_u64 v[64:65], s[18:19], 0, v[80:81]
	v_lshl_add_u64 v[64:65], s[36:37], 2, v[64:65]
	s_lshl_b32 s12, s50, 2
	v_lshl_add_u64 v[64:65], v[64:65], 0, s[12:13]
	global_store_dword v[64:65], v66, off
.LBB0_906:
	s_or_b64 exec, exec, s[2:3]
	v_add_u32_e32 v66, 0x80, v142
	v_ashrrev_i32_e32 v67, 31, v66
	v_lshlrev_b64 v[64:65], 6, v[66:67]
	v_lshl_add_u64 v[68:69], s[10:11], 0, v[64:65]
	v_bfe_u32 v78, v206, 4, 2
	v_lshlrev_b32_e32 v78, 4, v78
	v_mov_b32_e32 v79, 0
	v_lshl_add_u64 v[74:75], v[68:69], 0, v[78:79]
	global_load_dwordx4 v[70:73], v[74:75], off
	v_lshlrev_b64 v[66:67], 10, v[66:67]
	v_lshl_add_u64 v[66:67], v[66:67], 0, v[140:141]
	v_lshlrev_b64 v[66:67], 1, v[66:67]
	v_lshl_add_u64 v[68:69], s[20:21], 0, v[66:67]
	v_bfe_u32 v228, v206, 4, 1
	v_mul_u32_u24_e32 v228, 24, v228
	v_mov_b32_e32 v229, 0
	v_lshl_add_u64 v[230:231], v[68:69], 0, v[228:229]
	global_load_dwordx4 v[184:187], v[230:231], off
	v_lshl_add_u64 v[68:69], s[8:9], 0, v[66:67]
	v_bfe_u32 v228, v206, 4, 1
	v_mul_u32_u24_e32 v228, 24, v228
	v_mov_b32_e32 v229, 0
	v_lshl_add_u64 v[230:231], v[68:69], 0, v[228:229]
	global_load_dwordx4 v[188:191], v[230:231], off
	v_lshl_add_u64 v[90:91], s[16:17], 0, v[66:67]
	v_or_b32_e32 v92, 32, v66
	v_mov_b32_e32 v93, v67
	s_waitcnt vmcnt(0)
	v_permlane16_swap_b32_e32 v184, v186
	v_permlane16_swap_b32_e32 v185, v187
	v_permlane16_swap_b32_e32 v188, v190
	v_permlane16_swap_b32_e32 v189, v191
	v_add_f32_e32 v74, v70, v71
	v_add_f32_e32 v75, v72, v73
	v_add_f32_e32 v74, v74, v75
	ds_swizzle_b32 v75, v74 offset:swizzle(SWAP,16)
	s_waitcnt lgkmcnt(0)
	v_add_f32_e32 v74, v74, v75
	v_mov_b32_e32 v75, v74
	s_nop 1
	v_permlane32_swap_b32_e32 v74, v75
	v_add_f32_e32 v82, v74, v75
	v_lshlrev_b32_e32 v76, 16, v185
	v_lshlrev_b32_e32 v72, 16, v184
	v_mov_b32_e32 v70, v82
	v_fmamk_f32 v70, v70, 0x3a800000, v156
	v_mul_f32_e32 v71, 0x4b800000, v70
	v_cmp_gt_f32_e32 vcc, s56, v70
	v_and_b32_e32 v73, 0xffff0000, v184
	v_and_b32_e32 v77, 0xffff0000, v185
	v_cndmask_b32_e32 v70, v70, v71, vcc
	v_rsq_f32_e32 v74, v70
	s_waitcnt vmcnt(0)
	v_lshlrev_b32_e32 v70, 16, v188
	v_and_b32_e32 v71, 0xffff0000, v188
	v_mul_f32_e32 v75, 0x45800000, v74
	v_cndmask_b32_e32 v80, v74, v75, vcc
	v_mul_f32_e32 v60, v60, v80
	v_mul_f32_e32 v61, v61, v80
	v_mul_f32_e32 v62, v62, v80
	v_mul_f32_e32 v63, v63, v80
	v_mul_f32_e32 v60, 0xbfb8aa3b, v60
	v_mul_f32_e32 v61, 0xbfb8aa3b, v61
	v_mul_f32_e32 v62, 0xbfb8aa3b, v62
	v_mul_f32_e32 v63, 0xbfb8aa3b, v63
	v_exp_f32_e32 v60, v60
	v_exp_f32_e32 v61, v61
	v_exp_f32_e32 v62, v62
	v_exp_f32_e32 v63, v63
	v_add_f32_e32 v60, 1.0, v60
	v_add_f32_e32 v74, 1.0, v61
	v_add_f32_e32 v61, 1.0, v62
	v_add_f32_e32 v63, 1.0, v63
	v_rcp_f32_e32 v62, v60
	v_rcp_f32_e32 v60, v61
	v_rcp_f32_e32 v61, v63
	v_rcp_f32_e32 v63, v74
	v_lshlrev_b32_e32 v74, 16, v189
	v_and_b32_e32 v75, 0xffff0000, v189
	v_pk_fma_f32 v[60:61], v[60:61], v[76:77], v[74:75]
	v_pk_fma_f32 v[62:63], v[62:63], v[72:73], v[70:71]
	v_lshl_add_u64 v[74:75], s[20:21], 0, v[92:93]
	v_cvt_pk_bf16_f32 v70, v62, v63
	v_cvt_pk_bf16_f32 v71, v60, v61
	v_mov_b32_e32 v220, v70
	v_mov_b32_e32 v221, v71
	v_mul_f32_e32 v56, v56, v80
	v_mul_f32_e32 v57, v57, v80
	v_mul_f32_e32 v58, v58, v80
	v_mul_f32_e32 v59, v59, v80
	v_mul_f32_e32 v56, 0xbfb8aa3b, v56
	v_mul_f32_e32 v57, 0xbfb8aa3b, v57
	v_mul_f32_e32 v58, 0xbfb8aa3b, v58
	v_mul_f32_e32 v59, 0xbfb8aa3b, v59
	v_exp_f32_e32 v56, v56
	v_exp_f32_e32 v57, v57
	v_exp_f32_e32 v58, v58
	v_exp_f32_e32 v59, v59
	v_add_f32_e32 v56, 1.0, v56
	v_add_f32_e32 v57, 1.0, v57
	v_add_f32_e32 v58, 1.0, v58
	v_add_f32_e32 v59, 1.0, v59
	v_rcp_f32_e32 v56, v56
	v_rcp_f32_e32 v57, v57
	v_rcp_f32_e32 v58, v58
	v_rcp_f32_e32 v59, v59
	v_or_b32_e32 v74, 0x100, v66
	v_mov_b32_e32 v75, v67
	v_mul_f32_e32 v54, v54, v80
	v_mul_f32_e32 v55, v55, v80
	v_mul_f32_e32 v52, v52, v80
	v_mul_f32_e32 v53, v53, v80
	v_mul_f32_e32 v54, 0xbfb8aa3b, v54
	v_mul_f32_e32 v55, 0xbfb8aa3b, v55
	v_mul_f32_e32 v52, 0xbfb8aa3b, v52
	v_mul_f32_e32 v53, 0xbfb8aa3b, v53
	v_exp_f32_e32 v54, v54
	v_exp_f32_e32 v55, v55
	v_exp_f32_e32 v52, v52
	v_exp_f32_e32 v53, v53
	v_add_f32_e32 v54, 1.0, v54
	v_add_f32_e32 v55, 1.0, v55
	v_add_f32_e32 v52, 1.0, v52
	v_add_f32_e32 v53, 1.0, v53
	v_rcp_f32_e32 v54, v54
	v_rcp_f32_e32 v55, v55
	v_rcp_f32_e32 v52, v52
	v_rcp_f32_e32 v53, v53
	v_or_b32_e32 v66, 0x120, v66
	v_mul_f32_e32 v48, v48, v80
	v_mul_f32_e32 v49, v49, v80
	v_mul_f32_e32 v50, v50, v80
	v_mul_f32_e32 v51, v51, v80
	v_mul_f32_e32 v48, 0xbfb8aa3b, v48
	v_mul_f32_e32 v49, 0xbfb8aa3b, v49
	v_mul_f32_e32 v50, 0xbfb8aa3b, v50
	v_mul_f32_e32 v51, 0xbfb8aa3b, v51
	v_exp_f32_e32 v48, v48
	v_exp_f32_e32 v49, v49
	v_exp_f32_e32 v50, v50
	v_exp_f32_e32 v51, v51
	v_add_f32_e32 v48, 1.0, v48
	v_add_f32_e32 v49, 1.0, v49
	v_add_f32_e32 v50, 1.0, v50
	v_add_f32_e32 v51, 1.0, v51
	v_mul_f32_e32 v63, v63, v63
	v_mul_f32_e32 v61, v61, v61
	v_rcp_f32_e32 v48, v48
	v_rcp_f32_e32 v49, v49
	v_rcp_f32_e32 v50, v50
	v_rcp_f32_e32 v51, v51
	v_fmac_f32_e32 v63, v62, v62
	v_fmac_f32_e32 v61, v60, v60
	v_add_f32_e32 v60, v63, v61
	s_waitcnt vmcnt(0)
	v_lshlrev_b32_e32 v76, 16, v190
	v_and_b32_e32 v77, 0xffff0000, v190
	s_waitcnt vmcnt(0)
	v_lshlrev_b32_e32 v78, 16, v186
	v_and_b32_e32 v79, 0xffff0000, v186
	v_lshlrev_b32_e32 v72, 16, v191
	v_and_b32_e32 v73, 0xffff0000, v191
	v_lshlrev_b32_e32 v70, 16, v187
	v_and_b32_e32 v71, 0xffff0000, v187
	v_pk_fma_f32 v[56:57], v[56:57], v[78:79], v[76:77]
	v_lshl_add_u64 v[76:77], s[16:17], 0, v[92:93]
	v_pk_fma_f32 v[58:59], v[58:59], v[70:71], v[72:73]
	v_cvt_pk_bf16_f32 v70, v56, v57
	v_lshl_add_u64 v[78:79], s[20:21], 0, v[74:75]
	v_cvt_pk_bf16_f32 v71, v58, v59
	v_mov_b32_e32 v222, v70
	v_mov_b32_e32 v223, v71
	v_bfe_u32 v228, v206, 4, 1
	v_mul_u32_u24_e32 v228, 24, v228
	v_mov_b32_e32 v229, 0
	v_lshl_add_u64 v[230:231], v[76:77], 0, v[228:229]
	v_permlane16_swap_b32_e32 v220, v222
	v_permlane16_swap_b32_e32 v221, v223
	global_store_dwordx4 v[230:231], v[220:223], off offset:-32
	v_bfe_u32 v228, v206, 4, 1
	v_mul_u32_u24_e32 v228, 24, v228
	v_mov_b32_e32 v229, 0
	v_lshl_add_u64 v[230:231], v[68:69], 0, v[228:229]
	global_load_dwordx4 v[192:195], v[230:231], off offset:256
	v_mul_f32_e32 v57, v57, v57
	v_bfe_u32 v228, v206, 4, 1
	v_mul_u32_u24_e32 v228, 24, v228
	v_mov_b32_e32 v229, 0
	v_lshl_add_u64 v[230:231], v[78:79], 0, v[228:229]
	global_load_dwordx4 v[196:199], v[230:231], off
	v_mul_f32_e32 v59, v59, v59
	v_fmac_f32_e32 v57, v56, v56
	v_fmac_f32_e32 v59, v58, v58
	v_add_f32_e32 v56, v57, v59
	v_add_f32_e32 v56, v60, v56
	s_waitcnt vmcnt(0)
	v_permlane16_swap_b32_e32 v192, v194
	v_permlane16_swap_b32_e32 v193, v195
	v_permlane16_swap_b32_e32 v196, v198
	v_permlane16_swap_b32_e32 v197, v199
	v_lshlrev_b32_e32 v76, 16, v192
	v_and_b32_e32 v77, 0xffff0000, v192
	v_lshlrev_b32_e32 v72, 16, v193
	v_and_b32_e32 v73, 0xffff0000, v193
	s_waitcnt vmcnt(0)
	v_lshlrev_b32_e32 v78, 16, v196
	v_and_b32_e32 v79, 0xffff0000, v196
	v_lshlrev_b32_e32 v70, 16, v197
	v_and_b32_e32 v71, 0xffff0000, v197
	v_pk_fma_f32 v[54:55], v[54:55], v[70:71], v[72:73]
	v_lshl_add_u64 v[72:73], s[16:17], 0, v[74:75]
	v_pk_fma_f32 v[52:53], v[52:53], v[78:79], v[76:77]
	v_lshl_add_u64 v[74:75], s[20:21], 0, v[66:67]
	v_cvt_pk_bf16_f32 v70, v52, v53
	v_cvt_pk_bf16_f32 v71, v54, v55
	v_mov_b32_e32 v224, v70
	v_mov_b32_e32 v225, v71
	v_mul_f32_e32 v53, v53, v53
	v_mul_f32_e32 v55, v55, v55
	v_fmac_f32_e32 v53, v52, v52
	v_fmac_f32_e32 v55, v54, v54
	v_add_f32_e32 v52, v53, v55
	v_add_f32_e32 v60, v52, v56
	s_waitcnt vmcnt(0)
	v_lshlrev_b32_e32 v52, 16, v194
	v_and_b32_e32 v53, 0xffff0000, v194
	v_lshlrev_b32_e32 v54, 16, v195
	v_and_b32_e32 v55, 0xffff0000, v195
	s_waitcnt vmcnt(0)
	v_lshlrev_b32_e32 v56, 16, v198
	v_and_b32_e32 v57, 0xffff0000, v198
	v_lshlrev_b32_e32 v58, 16, v199
	v_and_b32_e32 v59, 0xffff0000, v199
	v_pk_fma_f32 v[50:51], v[50:51], v[58:59], v[54:55]
	v_pk_fma_f32 v[48:49], v[48:49], v[56:57], v[52:53]
	v_mul_f32_e32 v53, v51, v51
	v_mul_f32_e32 v52, v49, v49
	v_fmac_f32_e32 v52, v48, v48
	v_fmac_f32_e32 v53, v50, v50
	v_add_f32_e32 v52, v52, v53
	v_add_f32_e32 v54, v60, v52
	ds_swizzle_b32 v55, v54 offset:swizzle(SWAP,16)
	v_lshl_add_u64 v[52:53], s[16:17], 0, v[66:67]
	v_cvt_pk_bf16_f32 v48, v48, v49
	v_cvt_pk_bf16_f32 v49, v50, v51
	v_mov_b32_e32 v226, v48
	v_mov_b32_e32 v227, v49
	v_bfe_u32 v228, v206, 4, 1
	v_mul_u32_u24_e32 v228, 24, v228
	v_mov_b32_e32 v229, 0
	v_lshl_add_u64 v[230:231], v[52:53], 0, v[228:229]
	v_permlane16_swap_b32_e32 v224, v226
	v_permlane16_swap_b32_e32 v225, v227
	global_store_dwordx4 v[230:231], v[224:227], off offset:-32
	s_waitcnt lgkmcnt(0)
	v_add_f32_e32 v48, v54, v55
	v_mov_b32_e32 v49, v48
	s_nop 1
	v_permlane32_swap_b32_e32 v48, v49
	s_and_saveexec_b64 s[2:3], s[4:5]
	s_cbranch_execz .LBB0_908
	v_add_f32_e32 v50, v48, v49
	v_lshl_add_u64 v[48:49], s[18:19], 0, v[64:65]
	v_lshl_add_u64 v[48:49], s[36:37], 2, v[48:49]
	s_lshl_b32 s12, s50, 2
	v_lshl_add_u64 v[48:49], v[48:49], 0, s[12:13]
	global_store_dword v[48:49], v50, off
.LBB0_908:
	s_or_b64 exec, exec, s[2:3]
	v_add_u32_e32 v50, 0x90, v142
	v_ashrrev_i32_e32 v51, 31, v50
	v_lshlrev_b64 v[48:49], 6, v[50:51]
	v_lshl_add_u64 v[52:53], s[10:11], 0, v[48:49]
	v_bfe_u32 v62, v206, 4, 2
	v_lshlrev_b32_e32 v62, 4, v62
	v_mov_b32_e32 v63, 0
	v_lshl_add_u64 v[58:59], v[52:53], 0, v[62:63]
	global_load_dwordx4 v[54:57], v[58:59], off
	v_lshlrev_b64 v[50:51], 10, v[50:51]
	v_lshl_add_u64 v[50:51], v[50:51], 0, v[140:141]
	v_lshlrev_b64 v[50:51], 1, v[50:51]
	v_lshl_add_u64 v[52:53], s[20:21], 0, v[50:51]
	v_bfe_u32 v228, v206, 4, 1
	v_mul_u32_u24_e32 v228, 24, v228
	v_mov_b32_e32 v229, 0
	v_lshl_add_u64 v[230:231], v[52:53], 0, v[228:229]
	global_load_dwordx4 v[200:203], v[230:231], off
	v_lshl_add_u64 v[52:53], s[8:9], 0, v[50:51]
	v_bfe_u32 v228, v206, 4, 1
	v_mul_u32_u24_e32 v228, 24, v228
	v_mov_b32_e32 v229, 0
	v_lshl_add_u64 v[230:231], v[52:53], 0, v[228:229]
	global_load_dwordx4 v[208:211], v[230:231], off
	v_lshl_add_u64 v[74:75], s[16:17], 0, v[50:51]
	v_or_b32_e32 v76, 32, v50
	v_mov_b32_e32 v77, v51
	s_waitcnt vmcnt(0)
	v_permlane16_swap_b32_e32 v200, v202
	v_permlane16_swap_b32_e32 v201, v203
	v_permlane16_swap_b32_e32 v208, v210
	v_permlane16_swap_b32_e32 v209, v211
	v_add_f32_e32 v58, v54, v55
	v_add_f32_e32 v59, v56, v57
	v_add_f32_e32 v58, v58, v59
	ds_swizzle_b32 v59, v58 offset:swizzle(SWAP,16)
	s_waitcnt lgkmcnt(0)
	v_add_f32_e32 v58, v58, v59
	v_mov_b32_e32 v59, v58
	s_nop 1
	v_permlane32_swap_b32_e32 v58, v59
	v_add_f32_e32 v66, v58, v59
	v_lshlrev_b32_e32 v60, 16, v201
	v_lshlrev_b32_e32 v56, 16, v200
	v_mov_b32_e32 v54, v66
	v_fmamk_f32 v54, v54, 0x3a800000, v156
	v_mul_f32_e32 v55, 0x4b800000, v54
	v_cmp_gt_f32_e32 vcc, s56, v54
	v_and_b32_e32 v57, 0xffff0000, v200
	v_and_b32_e32 v61, 0xffff0000, v201
	v_cndmask_b32_e32 v54, v54, v55, vcc
	v_rsq_f32_e32 v58, v54
	s_waitcnt vmcnt(0)
	v_lshlrev_b32_e32 v54, 16, v208
	v_and_b32_e32 v55, 0xffff0000, v208
	v_mul_f32_e32 v59, 0x45800000, v58
	v_cndmask_b32_e32 v64, v58, v59, vcc
	v_mul_f32_e32 v44, v44, v64
	v_mul_f32_e32 v45, v45, v64
	v_mul_f32_e32 v46, v46, v64
	v_mul_f32_e32 v47, v47, v64
	v_mul_f32_e32 v44, 0xbfb8aa3b, v44
	v_mul_f32_e32 v45, 0xbfb8aa3b, v45
	v_mul_f32_e32 v46, 0xbfb8aa3b, v46
	v_mul_f32_e32 v47, 0xbfb8aa3b, v47
	v_exp_f32_e32 v44, v44
	v_exp_f32_e32 v45, v45
	v_exp_f32_e32 v46, v46
	v_exp_f32_e32 v47, v47
	v_add_f32_e32 v44, 1.0, v44
	v_add_f32_e32 v58, 1.0, v45
	v_add_f32_e32 v45, 1.0, v46
	v_add_f32_e32 v47, 1.0, v47
	v_rcp_f32_e32 v46, v44
	v_rcp_f32_e32 v44, v45
	v_rcp_f32_e32 v45, v47
	v_rcp_f32_e32 v47, v58
	v_lshlrev_b32_e32 v58, 16, v209
	v_and_b32_e32 v59, 0xffff0000, v209
	v_pk_fma_f32 v[44:45], v[44:45], v[60:61], v[58:59]
	v_pk_fma_f32 v[46:47], v[46:47], v[56:57], v[54:55]
	v_lshl_add_u64 v[58:59], s[20:21], 0, v[76:77]
	v_cvt_pk_bf16_f32 v54, v46, v47
	v_cvt_pk_bf16_f32 v55, v44, v45
	v_mov_b32_e32 v220, v54
	v_mov_b32_e32 v221, v55
	v_mul_f32_e32 v40, v40, v64
	v_mul_f32_e32 v41, v41, v64
	v_mul_f32_e32 v42, v42, v64
	v_mul_f32_e32 v43, v43, v64
	v_mul_f32_e32 v40, 0xbfb8aa3b, v40
	v_mul_f32_e32 v41, 0xbfb8aa3b, v41
	v_mul_f32_e32 v42, 0xbfb8aa3b, v42
	v_mul_f32_e32 v43, 0xbfb8aa3b, v43
	v_exp_f32_e32 v40, v40
	v_exp_f32_e32 v41, v41
	v_exp_f32_e32 v42, v42
	v_exp_f32_e32 v43, v43
	v_add_f32_e32 v40, 1.0, v40
	v_add_f32_e32 v41, 1.0, v41
	v_add_f32_e32 v42, 1.0, v42
	v_add_f32_e32 v43, 1.0, v43
	v_rcp_f32_e32 v40, v40
	v_rcp_f32_e32 v41, v41
	v_rcp_f32_e32 v42, v42
	v_rcp_f32_e32 v43, v43
	v_or_b32_e32 v58, 0x100, v50
	v_mov_b32_e32 v59, v51
	v_mul_f32_e32 v38, v38, v64
	v_mul_f32_e32 v39, v39, v64
	v_mul_f32_e32 v36, v36, v64
	v_mul_f32_e32 v37, v37, v64
	v_mul_f32_e32 v38, 0xbfb8aa3b, v38
	v_mul_f32_e32 v39, 0xbfb8aa3b, v39
	v_mul_f32_e32 v36, 0xbfb8aa3b, v36
	v_mul_f32_e32 v37, 0xbfb8aa3b, v37
	v_exp_f32_e32 v38, v38
	v_exp_f32_e32 v39, v39
	v_exp_f32_e32 v36, v36
	v_exp_f32_e32 v37, v37
	v_add_f32_e32 v38, 1.0, v38
	v_add_f32_e32 v39, 1.0, v39
	v_add_f32_e32 v36, 1.0, v36
	v_add_f32_e32 v37, 1.0, v37
	v_rcp_f32_e32 v38, v38
	v_rcp_f32_e32 v39, v39
	v_rcp_f32_e32 v36, v36
	v_rcp_f32_e32 v37, v37
	v_or_b32_e32 v50, 0x120, v50
	v_mul_f32_e32 v32, v32, v64
	v_mul_f32_e32 v33, v33, v64
	v_mul_f32_e32 v34, v34, v64
	v_mul_f32_e32 v35, v35, v64
	v_mul_f32_e32 v32, 0xbfb8aa3b, v32
	v_mul_f32_e32 v33, 0xbfb8aa3b, v33
	v_mul_f32_e32 v34, 0xbfb8aa3b, v34
	v_mul_f32_e32 v35, 0xbfb8aa3b, v35
	v_exp_f32_e32 v32, v32
	v_exp_f32_e32 v33, v33
	v_exp_f32_e32 v34, v34
	v_exp_f32_e32 v35, v35
	v_add_f32_e32 v32, 1.0, v32
	v_add_f32_e32 v33, 1.0, v33
	v_add_f32_e32 v34, 1.0, v34
	v_add_f32_e32 v35, 1.0, v35
	v_mul_f32_e32 v47, v47, v47
	v_mul_f32_e32 v45, v45, v45
	v_rcp_f32_e32 v32, v32
	v_rcp_f32_e32 v33, v33
	v_rcp_f32_e32 v34, v34
	v_rcp_f32_e32 v35, v35
	v_fmac_f32_e32 v47, v46, v46
	v_fmac_f32_e32 v45, v44, v44
	v_add_f32_e32 v44, v47, v45
	s_waitcnt vmcnt(0)
	v_lshlrev_b32_e32 v60, 16, v210
	v_and_b32_e32 v61, 0xffff0000, v210
	s_waitcnt vmcnt(0)
	v_lshlrev_b32_e32 v62, 16, v202
	v_and_b32_e32 v63, 0xffff0000, v202
	v_lshlrev_b32_e32 v56, 16, v211
	v_and_b32_e32 v57, 0xffff0000, v211
	v_lshlrev_b32_e32 v54, 16, v203
	v_and_b32_e32 v55, 0xffff0000, v203
	v_pk_fma_f32 v[40:41], v[40:41], v[62:63], v[60:61]
	v_lshl_add_u64 v[60:61], s[16:17], 0, v[76:77]
	v_pk_fma_f32 v[42:43], v[42:43], v[54:55], v[56:57]
	v_cvt_pk_bf16_f32 v54, v40, v41
	v_lshl_add_u64 v[62:63], s[20:21], 0, v[58:59]
	v_cvt_pk_bf16_f32 v55, v42, v43
	v_mov_b32_e32 v222, v54
	v_mov_b32_e32 v223, v55
	v_bfe_u32 v228, v206, 4, 1
	v_mul_u32_u24_e32 v228, 24, v228
	v_mov_b32_e32 v229, 0
	v_lshl_add_u64 v[230:231], v[60:61], 0, v[228:229]
	v_permlane16_swap_b32_e32 v220, v222
	v_permlane16_swap_b32_e32 v221, v223
	global_store_dwordx4 v[230:231], v[220:223], off offset:-32
	v_bfe_u32 v228, v206, 4, 1
	v_mul_u32_u24_e32 v228, 24, v228
	v_mov_b32_e32 v229, 0
	v_lshl_add_u64 v[230:231], v[52:53], 0, v[228:229]
	global_load_dwordx4 v[212:215], v[230:231], off offset:256
	v_mul_f32_e32 v41, v41, v41
	v_bfe_u32 v228, v206, 4, 1
	v_mul_u32_u24_e32 v228, 24, v228
	v_mov_b32_e32 v229, 0
	v_lshl_add_u64 v[230:231], v[62:63], 0, v[228:229]
	global_load_dwordx4 v[216:219], v[230:231], off
	v_mul_f32_e32 v43, v43, v43
	v_fmac_f32_e32 v41, v40, v40
	v_fmac_f32_e32 v43, v42, v42
	v_add_f32_e32 v40, v41, v43
	v_add_f32_e32 v40, v44, v40
	s_waitcnt vmcnt(0)
	v_permlane16_swap_b32_e32 v212, v214
	v_permlane16_swap_b32_e32 v213, v215
	v_permlane16_swap_b32_e32 v216, v218
	v_permlane16_swap_b32_e32 v217, v219
	v_lshlrev_b32_e32 v60, 16, v212
	v_and_b32_e32 v61, 0xffff0000, v212
	v_lshlrev_b32_e32 v56, 16, v213
	v_and_b32_e32 v57, 0xffff0000, v213
	s_waitcnt vmcnt(0)
	v_lshlrev_b32_e32 v62, 16, v216
	v_and_b32_e32 v63, 0xffff0000, v216
	v_lshlrev_b32_e32 v54, 16, v217
	v_and_b32_e32 v55, 0xffff0000, v217
	v_pk_fma_f32 v[38:39], v[38:39], v[54:55], v[56:57]
	v_lshl_add_u64 v[56:57], s[16:17], 0, v[58:59]
	v_pk_fma_f32 v[36:37], v[36:37], v[62:63], v[60:61]
	v_lshl_add_u64 v[58:59], s[20:21], 0, v[50:51]
	v_cvt_pk_bf16_f32 v54, v36, v37
	v_cvt_pk_bf16_f32 v55, v38, v39
	v_mov_b32_e32 v224, v54
	v_mov_b32_e32 v225, v55
	v_mul_f32_e32 v37, v37, v37
	v_mul_f32_e32 v39, v39, v39
	v_fmac_f32_e32 v37, v36, v36
	v_fmac_f32_e32 v39, v38, v38
	v_add_f32_e32 v36, v37, v39
	v_add_f32_e32 v44, v36, v40
	s_waitcnt vmcnt(0)
	v_lshlrev_b32_e32 v36, 16, v214
	v_and_b32_e32 v37, 0xffff0000, v214
	v_lshlrev_b32_e32 v38, 16, v215
	v_and_b32_e32 v39, 0xffff0000, v215
	s_waitcnt vmcnt(0)
	v_lshlrev_b32_e32 v40, 16, v218
	v_and_b32_e32 v41, 0xffff0000, v218
	v_lshlrev_b32_e32 v42, 16, v219
	v_and_b32_e32 v43, 0xffff0000, v219
	v_pk_fma_f32 v[34:35], v[34:35], v[42:43], v[38:39]
	v_pk_fma_f32 v[32:33], v[32:33], v[40:41], v[36:37]
	v_mul_f32_e32 v37, v35, v35
	v_mul_f32_e32 v36, v33, v33
	v_fmac_f32_e32 v36, v32, v32
	v_fmac_f32_e32 v37, v34, v34
	v_add_f32_e32 v36, v36, v37
	v_add_f32_e32 v38, v44, v36
	ds_swizzle_b32 v39, v38 offset:swizzle(SWAP,16)
	v_lshl_add_u64 v[36:37], s[16:17], 0, v[50:51]
	v_cvt_pk_bf16_f32 v32, v32, v33
	v_cvt_pk_bf16_f32 v33, v34, v35
	v_mov_b32_e32 v226, v32
	v_mov_b32_e32 v227, v33
	v_bfe_u32 v228, v206, 4, 1
	v_mul_u32_u24_e32 v228, 24, v228
	v_mov_b32_e32 v229, 0
	v_lshl_add_u64 v[230:231], v[36:37], 0, v[228:229]
	v_permlane16_swap_b32_e32 v224, v226
	v_permlane16_swap_b32_e32 v225, v227
	global_store_dwordx4 v[230:231], v[224:227], off offset:-32
	s_waitcnt lgkmcnt(0)
	v_add_f32_e32 v32, v38, v39
	v_mov_b32_e32 v33, v32
	s_nop 1
	v_permlane32_swap_b32_e32 v32, v33
	s_and_saveexec_b64 s[2:3], s[4:5]
	s_cbranch_execz .LBB0_910
	v_add_f32_e32 v34, v32, v33
	v_lshl_add_u64 v[32:33], s[18:19], 0, v[48:49]
	v_lshl_add_u64 v[32:33], s[36:37], 2, v[32:33]
	s_lshl_b32 s12, s50, 2
	v_lshl_add_u64 v[32:33], v[32:33], 0, s[12:13]
	global_store_dword v[32:33], v34, off
.LBB0_910:
	s_or_b64 exec, exec, s[2:3]
	v_add_u32_e32 v34, 0xa0, v142
	v_ashrrev_i32_e32 v35, 31, v34
	v_lshlrev_b64 v[32:33], 6, v[34:35]
	v_lshl_add_u64 v[36:37], s[10:11], 0, v[32:33]
	v_bfe_u32 v46, v206, 4, 2
	v_lshlrev_b32_e32 v46, 4, v46
	v_mov_b32_e32 v47, 0
	v_lshl_add_u64 v[42:43], v[36:37], 0, v[46:47]
	global_load_dwordx4 v[38:41], v[42:43], off
	v_lshlrev_b64 v[34:35], 10, v[34:35]
	v_lshl_add_u64 v[34:35], v[34:35], 0, v[140:141]
	v_lshlrev_b64 v[34:35], 1, v[34:35]
	v_lshl_add_u64 v[36:37], s[20:21], 0, v[34:35]
	v_bfe_u32 v228, v206, 4, 1
	v_mul_u32_u24_e32 v228, 24, v228
	v_mov_b32_e32 v229, 0
	v_lshl_add_u64 v[230:231], v[36:37], 0, v[228:229]
	global_load_dwordx4 v[184:187], v[230:231], off
	v_lshl_add_u64 v[36:37], s[8:9], 0, v[34:35]
	v_bfe_u32 v228, v206, 4, 1
	v_mul_u32_u24_e32 v228, 24, v228
	v_mov_b32_e32 v229, 0
	v_lshl_add_u64 v[230:231], v[36:37], 0, v[228:229]
	global_load_dwordx4 v[188:191], v[230:231], off
	v_lshl_add_u64 v[58:59], s[16:17], 0, v[34:35]
	v_or_b32_e32 v60, 32, v34
	v_mov_b32_e32 v61, v35
	s_waitcnt vmcnt(0)
	v_permlane16_swap_b32_e32 v184, v186
	v_permlane16_swap_b32_e32 v185, v187
	v_permlane16_swap_b32_e32 v188, v190
	v_permlane16_swap_b32_e32 v189, v191
	v_add_f32_e32 v42, v38, v39
	v_add_f32_e32 v43, v40, v41
	v_add_f32_e32 v42, v42, v43
	ds_swizzle_b32 v43, v42 offset:swizzle(SWAP,16)
	s_waitcnt lgkmcnt(0)
	v_add_f32_e32 v42, v42, v43
	v_mov_b32_e32 v43, v42
	s_nop 1
	v_permlane32_swap_b32_e32 v42, v43
	v_add_f32_e32 v50, v42, v43
	v_lshlrev_b32_e32 v44, 16, v185
	v_lshlrev_b32_e32 v40, 16, v184
	v_mov_b32_e32 v38, v50
	v_fmamk_f32 v38, v38, 0x3a800000, v156
	v_mul_f32_e32 v39, 0x4b800000, v38
	v_cmp_gt_f32_e32 vcc, s56, v38
	v_and_b32_e32 v41, 0xffff0000, v184
	v_and_b32_e32 v45, 0xffff0000, v185
	v_cndmask_b32_e32 v38, v38, v39, vcc
	v_rsq_f32_e32 v42, v38
	s_waitcnt vmcnt(0)
	v_lshlrev_b32_e32 v38, 16, v188
	v_and_b32_e32 v39, 0xffff0000, v188
	v_mul_f32_e32 v43, 0x45800000, v42
	v_cndmask_b32_e32 v48, v42, v43, vcc
	v_mul_f32_e32 v28, v28, v48
	v_mul_f32_e32 v29, v29, v48
	v_mul_f32_e32 v30, v30, v48
	v_mul_f32_e32 v31, v31, v48
	v_mul_f32_e32 v28, 0xbfb8aa3b, v28
	v_mul_f32_e32 v29, 0xbfb8aa3b, v29
	v_mul_f32_e32 v30, 0xbfb8aa3b, v30
	v_mul_f32_e32 v31, 0xbfb8aa3b, v31
	v_exp_f32_e32 v28, v28
	v_exp_f32_e32 v29, v29
	v_exp_f32_e32 v30, v30
	v_exp_f32_e32 v31, v31
	v_add_f32_e32 v28, 1.0, v28
	v_add_f32_e32 v42, 1.0, v29
	v_add_f32_e32 v29, 1.0, v30
	v_add_f32_e32 v31, 1.0, v31
	v_rcp_f32_e32 v30, v28
	v_rcp_f32_e32 v28, v29
	v_rcp_f32_e32 v29, v31
	v_rcp_f32_e32 v31, v42
	v_lshlrev_b32_e32 v42, 16, v189
	v_and_b32_e32 v43, 0xffff0000, v189
	v_pk_fma_f32 v[28:29], v[28:29], v[44:45], v[42:43]
	v_pk_fma_f32 v[30:31], v[30:31], v[40:41], v[38:39]
	v_lshl_add_u64 v[42:43], s[20:21], 0, v[60:61]
	v_cvt_pk_bf16_f32 v38, v30, v31
	v_cvt_pk_bf16_f32 v39, v28, v29
	v_mov_b32_e32 v220, v38
	v_mov_b32_e32 v221, v39
	v_mul_f32_e32 v24, v24, v48
	v_mul_f32_e32 v25, v25, v48
	v_mul_f32_e32 v26, v26, v48
	v_mul_f32_e32 v27, v27, v48
	v_mul_f32_e32 v24, 0xbfb8aa3b, v24
	v_mul_f32_e32 v25, 0xbfb8aa3b, v25
	v_mul_f32_e32 v26, 0xbfb8aa3b, v26
	v_mul_f32_e32 v27, 0xbfb8aa3b, v27
	v_exp_f32_e32 v24, v24
	v_exp_f32_e32 v25, v25
	v_exp_f32_e32 v26, v26
	v_exp_f32_e32 v27, v27
	v_add_f32_e32 v24, 1.0, v24
	v_add_f32_e32 v25, 1.0, v25
	v_add_f32_e32 v26, 1.0, v26
	v_add_f32_e32 v27, 1.0, v27
	v_rcp_f32_e32 v24, v24
	v_rcp_f32_e32 v25, v25
	v_rcp_f32_e32 v26, v26
	v_rcp_f32_e32 v27, v27
	v_or_b32_e32 v42, 0x100, v34
	v_mov_b32_e32 v43, v35
	v_mul_f32_e32 v22, v22, v48
	v_mul_f32_e32 v23, v23, v48
	v_mul_f32_e32 v20, v20, v48
	v_mul_f32_e32 v21, v21, v48
	v_mul_f32_e32 v22, 0xbfb8aa3b, v22
	v_mul_f32_e32 v23, 0xbfb8aa3b, v23
	v_mul_f32_e32 v20, 0xbfb8aa3b, v20
	v_mul_f32_e32 v21, 0xbfb8aa3b, v21
	v_exp_f32_e32 v22, v22
	v_exp_f32_e32 v23, v23
	v_exp_f32_e32 v20, v20
	v_exp_f32_e32 v21, v21
	v_add_f32_e32 v22, 1.0, v22
	v_add_f32_e32 v23, 1.0, v23
	v_add_f32_e32 v20, 1.0, v20
	v_add_f32_e32 v21, 1.0, v21
	v_rcp_f32_e32 v22, v22
	v_rcp_f32_e32 v23, v23
	v_rcp_f32_e32 v20, v20
	v_rcp_f32_e32 v21, v21
	v_or_b32_e32 v34, 0x120, v34
	v_mul_f32_e32 v16, v16, v48
	v_mul_f32_e32 v17, v17, v48
	v_mul_f32_e32 v18, v18, v48
	v_mul_f32_e32 v19, v19, v48
	v_mul_f32_e32 v16, 0xbfb8aa3b, v16
	v_mul_f32_e32 v17, 0xbfb8aa3b, v17
	v_mul_f32_e32 v18, 0xbfb8aa3b, v18
	v_mul_f32_e32 v19, 0xbfb8aa3b, v19
	v_exp_f32_e32 v16, v16
	v_exp_f32_e32 v17, v17
	v_exp_f32_e32 v18, v18
	v_exp_f32_e32 v19, v19
	v_add_f32_e32 v16, 1.0, v16
	v_add_f32_e32 v17, 1.0, v17
	v_add_f32_e32 v18, 1.0, v18
	v_add_f32_e32 v19, 1.0, v19
	v_mul_f32_e32 v31, v31, v31
	v_mul_f32_e32 v29, v29, v29
	v_rcp_f32_e32 v16, v16
	v_rcp_f32_e32 v17, v17
	v_rcp_f32_e32 v18, v18
	v_rcp_f32_e32 v19, v19
	v_fmac_f32_e32 v31, v30, v30
	v_fmac_f32_e32 v29, v28, v28
	v_add_f32_e32 v28, v31, v29
	s_waitcnt vmcnt(0)
	v_lshlrev_b32_e32 v44, 16, v190
	v_and_b32_e32 v45, 0xffff0000, v190
	s_waitcnt vmcnt(0)
	v_lshlrev_b32_e32 v46, 16, v186
	v_and_b32_e32 v47, 0xffff0000, v186
	v_lshlrev_b32_e32 v40, 16, v191
	v_and_b32_e32 v41, 0xffff0000, v191
	v_lshlrev_b32_e32 v38, 16, v187
	v_and_b32_e32 v39, 0xffff0000, v187
	v_pk_fma_f32 v[24:25], v[24:25], v[46:47], v[44:45]
	v_lshl_add_u64 v[44:45], s[16:17], 0, v[60:61]
	v_pk_fma_f32 v[26:27], v[26:27], v[38:39], v[40:41]
	v_cvt_pk_bf16_f32 v38, v24, v25
	v_lshl_add_u64 v[46:47], s[20:21], 0, v[42:43]
	v_cvt_pk_bf16_f32 v39, v26, v27
	v_mov_b32_e32 v222, v38
	v_mov_b32_e32 v223, v39
	v_bfe_u32 v228, v206, 4, 1
	v_mul_u32_u24_e32 v228, 24, v228
	v_mov_b32_e32 v229, 0
	v_lshl_add_u64 v[230:231], v[44:45], 0, v[228:229]
	v_permlane16_swap_b32_e32 v220, v222
	v_permlane16_swap_b32_e32 v221, v223
	global_store_dwordx4 v[230:231], v[220:223], off offset:-32
	v_bfe_u32 v228, v206, 4, 1
	v_mul_u32_u24_e32 v228, 24, v228
	v_mov_b32_e32 v229, 0
	v_lshl_add_u64 v[230:231], v[36:37], 0, v[228:229]
	global_load_dwordx4 v[192:195], v[230:231], off offset:256
	v_mul_f32_e32 v25, v25, v25
	v_bfe_u32 v228, v206, 4, 1
	v_mul_u32_u24_e32 v228, 24, v228
	v_mov_b32_e32 v229, 0
	v_lshl_add_u64 v[230:231], v[46:47], 0, v[228:229]
	global_load_dwordx4 v[196:199], v[230:231], off
	v_mul_f32_e32 v27, v27, v27
	v_fmac_f32_e32 v25, v24, v24
	v_fmac_f32_e32 v27, v26, v26
	v_add_f32_e32 v24, v25, v27
	v_add_f32_e32 v24, v28, v24
	s_waitcnt vmcnt(0)
	v_permlane16_swap_b32_e32 v192, v194
	v_permlane16_swap_b32_e32 v193, v195
	v_permlane16_swap_b32_e32 v196, v198
	v_permlane16_swap_b32_e32 v197, v199
	v_lshlrev_b32_e32 v44, 16, v192
	v_and_b32_e32 v45, 0xffff0000, v192
	v_lshlrev_b32_e32 v40, 16, v193
	v_and_b32_e32 v41, 0xffff0000, v193
	s_waitcnt vmcnt(0)
	v_lshlrev_b32_e32 v46, 16, v196
	v_and_b32_e32 v47, 0xffff0000, v196
	v_lshlrev_b32_e32 v38, 16, v197
	v_and_b32_e32 v39, 0xffff0000, v197
	v_pk_fma_f32 v[22:23], v[22:23], v[38:39], v[40:41]
	v_lshl_add_u64 v[40:41], s[16:17], 0, v[42:43]
	v_pk_fma_f32 v[20:21], v[20:21], v[46:47], v[44:45]
	v_lshl_add_u64 v[42:43], s[20:21], 0, v[34:35]
	v_cvt_pk_bf16_f32 v38, v20, v21
	v_cvt_pk_bf16_f32 v39, v22, v23
	v_mov_b32_e32 v224, v38
	v_mov_b32_e32 v225, v39
	v_mul_f32_e32 v21, v21, v21
	v_mul_f32_e32 v23, v23, v23
	v_fmac_f32_e32 v21, v20, v20
	v_fmac_f32_e32 v23, v22, v22
	v_add_f32_e32 v20, v21, v23
	v_add_f32_e32 v28, v20, v24
	s_waitcnt vmcnt(0)
	v_lshlrev_b32_e32 v20, 16, v194
	v_and_b32_e32 v21, 0xffff0000, v194
	v_lshlrev_b32_e32 v22, 16, v195
	v_and_b32_e32 v23, 0xffff0000, v195
	s_waitcnt vmcnt(0)
	v_lshlrev_b32_e32 v24, 16, v198
	v_and_b32_e32 v25, 0xffff0000, v198
	v_lshlrev_b32_e32 v26, 16, v199
	v_and_b32_e32 v27, 0xffff0000, v199
	v_pk_fma_f32 v[18:19], v[18:19], v[26:27], v[22:23]
	v_pk_fma_f32 v[16:17], v[16:17], v[24:25], v[20:21]
	v_mul_f32_e32 v21, v19, v19
	v_mul_f32_e32 v20, v17, v17
	v_fmac_f32_e32 v20, v16, v16
	v_fmac_f32_e32 v21, v18, v18
	v_add_f32_e32 v20, v20, v21
	v_add_f32_e32 v22, v28, v20
	ds_swizzle_b32 v23, v22 offset:swizzle(SWAP,16)
	v_lshl_add_u64 v[20:21], s[16:17], 0, v[34:35]
	v_cvt_pk_bf16_f32 v16, v16, v17
	v_cvt_pk_bf16_f32 v17, v18, v19
	v_mov_b32_e32 v226, v16
	v_mov_b32_e32 v227, v17
	v_bfe_u32 v228, v206, 4, 1
	v_mul_u32_u24_e32 v228, 24, v228
	v_mov_b32_e32 v229, 0
	v_lshl_add_u64 v[230:231], v[20:21], 0, v[228:229]
	v_permlane16_swap_b32_e32 v224, v226
	v_permlane16_swap_b32_e32 v225, v227
	global_store_dwordx4 v[230:231], v[224:227], off offset:-32
	s_waitcnt lgkmcnt(0)
	v_add_f32_e32 v16, v22, v23
	v_mov_b32_e32 v17, v16
	s_nop 1
	v_permlane32_swap_b32_e32 v16, v17
	s_and_saveexec_b64 s[2:3], s[4:5]
	s_cbranch_execz .LBB0_912
	v_add_f32_e32 v18, v16, v17
	v_lshl_add_u64 v[16:17], s[18:19], 0, v[32:33]
	v_lshl_add_u64 v[16:17], s[36:37], 2, v[16:17]
	s_lshl_b32 s12, s50, 2
	v_lshl_add_u64 v[16:17], v[16:17], 0, s[12:13]
	global_store_dword v[16:17], v18, off
.LBB0_912:
	s_or_b64 exec, exec, s[2:3]
	v_add_u32_e32 v18, 0xb0, v142
	v_ashrrev_i32_e32 v19, 31, v18
	v_lshlrev_b64 v[16:17], 6, v[18:19]
	v_lshl_add_u64 v[20:21], s[10:11], 0, v[16:17]
	v_bfe_u32 v30, v206, 4, 2
	v_lshlrev_b32_e32 v30, 4, v30
	v_mov_b32_e32 v31, 0
	v_lshl_add_u64 v[26:27], v[20:21], 0, v[30:31]
	global_load_dwordx4 v[22:25], v[26:27], off
	v_lshlrev_b64 v[18:19], 10, v[18:19]
	v_lshl_add_u64 v[18:19], v[18:19], 0, v[140:141]
	v_lshlrev_b64 v[18:19], 1, v[18:19]
	v_lshl_add_u64 v[20:21], s[20:21], 0, v[18:19]
	v_bfe_u32 v228, v206, 4, 1
	v_mul_u32_u24_e32 v228, 24, v228
	v_mov_b32_e32 v229, 0
	v_lshl_add_u64 v[230:231], v[20:21], 0, v[228:229]
	global_load_dwordx4 v[200:203], v[230:231], off
	v_lshl_add_u64 v[20:21], s[8:9], 0, v[18:19]
	v_bfe_u32 v228, v206, 4, 1
	v_mul_u32_u24_e32 v228, 24, v228
	v_mov_b32_e32 v229, 0
	v_lshl_add_u64 v[230:231], v[20:21], 0, v[228:229]
	global_load_dwordx4 v[208:211], v[230:231], off
	v_lshl_add_u64 v[42:43], s[16:17], 0, v[18:19]
	v_or_b32_e32 v44, 32, v18
	v_mov_b32_e32 v45, v19
	s_waitcnt vmcnt(0)
	v_permlane16_swap_b32_e32 v200, v202
	v_permlane16_swap_b32_e32 v201, v203
	v_permlane16_swap_b32_e32 v208, v210
	v_permlane16_swap_b32_e32 v209, v211
	v_add_f32_e32 v26, v22, v23
	v_add_f32_e32 v27, v24, v25
	v_add_f32_e32 v26, v26, v27
	ds_swizzle_b32 v27, v26 offset:swizzle(SWAP,16)
	s_waitcnt lgkmcnt(0)
	v_add_f32_e32 v26, v26, v27
	v_mov_b32_e32 v27, v26
	s_nop 1
	v_permlane32_swap_b32_e32 v26, v27
	v_add_f32_e32 v34, v26, v27
	v_lshlrev_b32_e32 v28, 16, v201
	v_lshlrev_b32_e32 v24, 16, v200
	v_mov_b32_e32 v22, v34
	v_fmamk_f32 v22, v22, 0x3a800000, v156
	v_mul_f32_e32 v23, 0x4b800000, v22
	v_cmp_gt_f32_e32 vcc, s56, v22
	v_and_b32_e32 v25, 0xffff0000, v200
	v_and_b32_e32 v29, 0xffff0000, v201
	v_cndmask_b32_e32 v22, v22, v23, vcc
	v_rsq_f32_e32 v26, v22
	s_waitcnt vmcnt(0)
	v_lshlrev_b32_e32 v22, 16, v208
	v_and_b32_e32 v23, 0xffff0000, v208
	v_mul_f32_e32 v27, 0x45800000, v26
	v_cndmask_b32_e32 v32, v26, v27, vcc
	v_mul_f32_e32 v12, v12, v32
	v_mul_f32_e32 v13, v13, v32
	v_mul_f32_e32 v14, v14, v32
	v_mul_f32_e32 v15, v15, v32
	v_mul_f32_e32 v12, 0xbfb8aa3b, v12
	v_mul_f32_e32 v13, 0xbfb8aa3b, v13
	v_mul_f32_e32 v14, 0xbfb8aa3b, v14
	v_mul_f32_e32 v15, 0xbfb8aa3b, v15
	v_exp_f32_e32 v12, v12
	v_exp_f32_e32 v13, v13
	v_exp_f32_e32 v14, v14
	v_exp_f32_e32 v15, v15
	v_add_f32_e32 v12, 1.0, v12
	v_add_f32_e32 v26, 1.0, v13
	v_add_f32_e32 v13, 1.0, v14
	v_add_f32_e32 v15, 1.0, v15
	v_rcp_f32_e32 v14, v12
	v_rcp_f32_e32 v12, v13
	v_rcp_f32_e32 v13, v15
	v_rcp_f32_e32 v15, v26
	v_lshlrev_b32_e32 v26, 16, v209
	v_and_b32_e32 v27, 0xffff0000, v209
	v_pk_fma_f32 v[12:13], v[12:13], v[28:29], v[26:27]
	v_pk_fma_f32 v[14:15], v[14:15], v[24:25], v[22:23]
	v_lshl_add_u64 v[26:27], s[20:21], 0, v[44:45]
	v_cvt_pk_bf16_f32 v22, v14, v15
	v_cvt_pk_bf16_f32 v23, v12, v13
	v_mov_b32_e32 v220, v22
	v_mov_b32_e32 v221, v23
	v_mul_f32_e32 v8, v8, v32
	v_mul_f32_e32 v9, v9, v32
	v_mul_f32_e32 v10, v10, v32
	v_mul_f32_e32 v11, v11, v32
	v_mul_f32_e32 v8, 0xbfb8aa3b, v8
	v_mul_f32_e32 v9, 0xbfb8aa3b, v9
	v_mul_f32_e32 v10, 0xbfb8aa3b, v10
	v_mul_f32_e32 v11, 0xbfb8aa3b, v11
	v_exp_f32_e32 v8, v8
	v_exp_f32_e32 v9, v9
	v_exp_f32_e32 v10, v10
	v_exp_f32_e32 v11, v11
	v_add_f32_e32 v8, 1.0, v8
	v_add_f32_e32 v9, 1.0, v9
	v_add_f32_e32 v10, 1.0, v10
	v_add_f32_e32 v11, 1.0, v11
	v_rcp_f32_e32 v8, v8
	v_rcp_f32_e32 v9, v9
	v_rcp_f32_e32 v10, v10
	v_rcp_f32_e32 v11, v11
	v_or_b32_e32 v26, 0x100, v18
	v_mov_b32_e32 v27, v19
	v_mul_f32_e32 v6, v6, v32
	v_mul_f32_e32 v7, v7, v32
	v_mul_f32_e32 v4, v4, v32
	v_mul_f32_e32 v5, v5, v32
	v_mul_f32_e32 v6, 0xbfb8aa3b, v6
	v_mul_f32_e32 v7, 0xbfb8aa3b, v7
	v_mul_f32_e32 v4, 0xbfb8aa3b, v4
	v_mul_f32_e32 v5, 0xbfb8aa3b, v5
	v_exp_f32_e32 v6, v6
	v_exp_f32_e32 v7, v7
	v_exp_f32_e32 v4, v4
	v_exp_f32_e32 v5, v5
	v_add_f32_e32 v6, 1.0, v6
	v_add_f32_e32 v7, 1.0, v7
	v_add_f32_e32 v4, 1.0, v4
	v_add_f32_e32 v5, 1.0, v5
	v_rcp_f32_e32 v6, v6
	v_rcp_f32_e32 v7, v7
	v_rcp_f32_e32 v4, v4
	v_rcp_f32_e32 v5, v5
	v_or_b32_e32 v18, 0x120, v18
	v_mul_f32_e32 v0, v0, v32
	v_mul_f32_e32 v1, v1, v32
	v_mul_f32_e32 v2, v2, v32
	v_mul_f32_e32 v3, v3, v32
	v_mul_f32_e32 v0, 0xbfb8aa3b, v0
	v_mul_f32_e32 v1, 0xbfb8aa3b, v1
	v_mul_f32_e32 v2, 0xbfb8aa3b, v2
	v_mul_f32_e32 v3, 0xbfb8aa3b, v3
	v_exp_f32_e32 v0, v0
	v_exp_f32_e32 v1, v1
	v_exp_f32_e32 v2, v2
	v_exp_f32_e32 v3, v3
	v_add_f32_e32 v0, 1.0, v0
	v_add_f32_e32 v1, 1.0, v1
	v_add_f32_e32 v2, 1.0, v2
	v_add_f32_e32 v3, 1.0, v3
	v_mul_f32_e32 v15, v15, v15
	v_mul_f32_e32 v13, v13, v13
	v_rcp_f32_e32 v0, v0
	v_rcp_f32_e32 v1, v1
	v_rcp_f32_e32 v2, v2
	v_rcp_f32_e32 v3, v3
	v_fmac_f32_e32 v15, v14, v14
	v_fmac_f32_e32 v13, v12, v12
	v_add_f32_e32 v12, v15, v13
	s_waitcnt vmcnt(0)
	v_lshlrev_b32_e32 v28, 16, v210
	v_and_b32_e32 v29, 0xffff0000, v210
	s_waitcnt vmcnt(0)
	v_lshlrev_b32_e32 v30, 16, v202
	v_and_b32_e32 v31, 0xffff0000, v202
	v_lshlrev_b32_e32 v24, 16, v211
	v_and_b32_e32 v25, 0xffff0000, v211
	v_lshlrev_b32_e32 v22, 16, v203
	v_and_b32_e32 v23, 0xffff0000, v203
	v_pk_fma_f32 v[8:9], v[8:9], v[30:31], v[28:29]
	v_lshl_add_u64 v[28:29], s[16:17], 0, v[44:45]
	v_pk_fma_f32 v[10:11], v[10:11], v[22:23], v[24:25]
	v_cvt_pk_bf16_f32 v22, v8, v9
	v_lshl_add_u64 v[30:31], s[20:21], 0, v[26:27]
	v_cvt_pk_bf16_f32 v23, v10, v11
	v_mov_b32_e32 v222, v22
	v_mov_b32_e32 v223, v23
	v_bfe_u32 v228, v206, 4, 1
	v_mul_u32_u24_e32 v228, 24, v228
	v_mov_b32_e32 v229, 0
	v_lshl_add_u64 v[230:231], v[28:29], 0, v[228:229]
	v_permlane16_swap_b32_e32 v220, v222
	v_permlane16_swap_b32_e32 v221, v223
	global_store_dwordx4 v[230:231], v[220:223], off offset:-32
	v_bfe_u32 v228, v206, 4, 1
	v_mul_u32_u24_e32 v228, 24, v228
	v_mov_b32_e32 v229, 0
	v_lshl_add_u64 v[230:231], v[20:21], 0, v[228:229]
	global_load_dwordx4 v[212:215], v[230:231], off offset:256
	v_mul_f32_e32 v9, v9, v9
	v_bfe_u32 v228, v206, 4, 1
	v_mul_u32_u24_e32 v228, 24, v228
	v_mov_b32_e32 v229, 0
	v_lshl_add_u64 v[230:231], v[30:31], 0, v[228:229]
	global_load_dwordx4 v[216:219], v[230:231], off
	v_mul_f32_e32 v11, v11, v11
	v_fmac_f32_e32 v9, v8, v8
	v_fmac_f32_e32 v11, v10, v10
	v_add_f32_e32 v8, v9, v11
	v_add_f32_e32 v8, v12, v8
	s_waitcnt vmcnt(0)
	v_permlane16_swap_b32_e32 v212, v214
	v_permlane16_swap_b32_e32 v213, v215
	v_permlane16_swap_b32_e32 v216, v218
	v_permlane16_swap_b32_e32 v217, v219
	v_lshlrev_b32_e32 v28, 16, v212
	v_and_b32_e32 v29, 0xffff0000, v212
	v_lshlrev_b32_e32 v24, 16, v213
	v_and_b32_e32 v25, 0xffff0000, v213
	s_waitcnt vmcnt(0)
	v_lshlrev_b32_e32 v30, 16, v216
	v_and_b32_e32 v31, 0xffff0000, v216
	v_lshlrev_b32_e32 v22, 16, v217
	v_and_b32_e32 v23, 0xffff0000, v217
	v_pk_fma_f32 v[6:7], v[6:7], v[22:23], v[24:25]
	v_lshl_add_u64 v[24:25], s[16:17], 0, v[26:27]
	v_pk_fma_f32 v[4:5], v[4:5], v[30:31], v[28:29]
	v_lshl_add_u64 v[26:27], s[20:21], 0, v[18:19]
	v_cvt_pk_bf16_f32 v22, v4, v5
	v_cvt_pk_bf16_f32 v23, v6, v7
	v_mov_b32_e32 v224, v22
	v_mov_b32_e32 v225, v23
	v_mul_f32_e32 v5, v5, v5
	v_mul_f32_e32 v7, v7, v7
	v_fmac_f32_e32 v5, v4, v4
	v_fmac_f32_e32 v7, v6, v6
	v_add_f32_e32 v4, v5, v7
	v_add_f32_e32 v12, v4, v8
	s_waitcnt vmcnt(0)
	v_lshlrev_b32_e32 v4, 16, v214
	v_and_b32_e32 v5, 0xffff0000, v214
	v_lshlrev_b32_e32 v6, 16, v215
	v_and_b32_e32 v7, 0xffff0000, v215
	s_waitcnt vmcnt(0)
	v_lshlrev_b32_e32 v8, 16, v218
	v_and_b32_e32 v9, 0xffff0000, v218
	v_lshlrev_b32_e32 v10, 16, v219
	v_and_b32_e32 v11, 0xffff0000, v219
	v_pk_fma_f32 v[2:3], v[2:3], v[10:11], v[6:7]
	v_pk_fma_f32 v[0:1], v[0:1], v[8:9], v[4:5]
	v_mul_f32_e32 v5, v3, v3
	v_mul_f32_e32 v4, v1, v1
	v_fmac_f32_e32 v4, v0, v0
	v_fmac_f32_e32 v5, v2, v2
	v_add_f32_e32 v4, v4, v5
	v_add_f32_e32 v6, v12, v4
	ds_swizzle_b32 v7, v6 offset:swizzle(SWAP,16)
	v_lshl_add_u64 v[4:5], s[16:17], 0, v[18:19]
	v_cvt_pk_bf16_f32 v0, v0, v1
	v_cvt_pk_bf16_f32 v1, v2, v3
	v_mov_b32_e32 v226, v0
	v_mov_b32_e32 v227, v1
	v_bfe_u32 v228, v206, 4, 1
	v_mul_u32_u24_e32 v228, 24, v228
	v_mov_b32_e32 v229, 0
	v_lshl_add_u64 v[230:231], v[4:5], 0, v[228:229]
	v_permlane16_swap_b32_e32 v224, v226
	v_permlane16_swap_b32_e32 v225, v227
	global_store_dwordx4 v[230:231], v[224:227], off offset:-32
	s_waitcnt lgkmcnt(0)
	v_add_f32_e32 v0, v6, v7
	v_mov_b32_e32 v1, v0
	s_nop 1
	v_permlane32_swap_b32_e32 v0, v1
	s_and_saveexec_b64 s[2:3], s[4:5]
	s_cbranch_execz .LBB0_914
	v_add_f32_e32 v2, v0, v1
	v_lshl_add_u64 v[0:1], s[18:19], 0, v[16:17]
	v_lshl_add_u64 v[0:1], s[36:37], 2, v[0:1]
	s_lshl_b32 s12, s50, 2
	v_lshl_add_u64 v[0:1], v[0:1], 0, s[12:13]
	global_store_dword v[0:1], v2, off
